# baseline (speedup 1.0000x reference)
; __device__ __forceinline__ float sigmoidf_(float z) { return __builtin_amdgcn_rcpf(1.f + __builtin_amdgcn_exp2f(-LOG2E_ * z)); }
; #define EPI_LOOP_END asm volatile("" ::: "memory"); } }
; __device__ __forceinline__ u32x4 pack8(const f32x4 a, const f32x4 b) { u32x4 w; w.x = pk2(a[0], a[1]); w.y = pk2(a[2], a[3]); w.z = pk2(b[0], b[1]); w.w = pk2(b[2], b[3]); return w; }
;     __device__ __forceinline__ bf16_t* u(int n) const { return (bf16_t*)(ws + WS_ARENA + (size_t)n * UNIT); }
;     __device__ __forceinline__ void operator()(const f32x4 (&acc)[2][2][4][2], const Unit& u, int wr, int wc, int fr, int fq) const {
;         EPI_LOOP_BEGIN
;             const f32x4 b0 = *(const f32x4*)(bias + col), b1 = *(const f32x4*)(bias + col + 4); f32x4 a, b;
; #pragma unroll
;             for (int j = 0; j < 4; ++j) { a[j] = sigmoidf_(v0[j] + b0[j]); b[j] = sigmoidf_(v1[j] + b1[j]); if (MODE == 0) { a[j] *= -0.6065306597126334f; b[j] *= -0.6065306597126334f; } }
;             *(u32x4*)(O + (size_t)row * DM + col) = pack8(a, b);
;         EPI_LOOP_END
.LBB0_1522:
	v_lshl_or_b32 v150, s81, 8, v167
	v_ashrrev_i32_e32 v151, 31, v150
	v_lshl_add_u64 v[146:147], v[150:151], 2, s[10:11]
	global_load_dwordx4 v[200:203], v[146:147], off
	global_load_dwordx4 v[204:207], v[146:147], off offset:16
	global_load_dwordx4 v[208:211], v[146:147], off offset:512
	global_load_dwordx4 v[212:215], v[146:147], off offset:528
	v_lshl_add_u32 v148, s80, 8, v165
	v_ashrrev_i32_e32 v149, 31, v148
	v_lshlrev_b64 v[180:181], 12, v[148:149]
	v_lshlrev_b64 v[150:151], 1, v[150:151]
	v_lshl_add_u64 v[180:181], s[22:23], 0, v[180:181]
	v_lshl_add_u64 v[180:181], v[180:181], 0, v[150:151]
	s_and_b64 vcc, exec, s[0:1]
	s_mov_b64 s[0:1], -1
	s_waitcnt vmcnt(0)
	v_mov_b64_e32 v[172:173], v[200:201]
	v_mov_b64_e32 v[174:175], v[202:203]
	v_mov_b64_e32 v[176:177], v[204:205]
	v_mov_b64_e32 v[178:179], v[206:207]
	v_add_f32_e32 v122, v122, v172
	v_add_f32_e32 v126, v126, v176
	v_add_f32_e32 v123, v123, v173
	v_add_f32_e32 v127, v127, v177
	v_add_f32_e32 v124, v124, v174
	v_add_f32_e32 v128, v128, v178
	v_add_f32_e32 v125, v125, v175
	v_add_f32_e32 v129, v129, v179
	v_mul_f32_e32 v122, 0xbfb8aa3b, v122
	v_mul_f32_e32 v126, 0xbfb8aa3b, v126
	v_mul_f32_e32 v123, 0xbfb8aa3b, v123
	v_mul_f32_e32 v127, 0xbfb8aa3b, v127
	v_mul_f32_e32 v124, 0xbfb8aa3b, v124
	v_mul_f32_e32 v128, 0xbfb8aa3b, v128
	v_mul_f32_e32 v125, 0xbfb8aa3b, v125
	v_mul_f32_e32 v129, 0xbfb8aa3b, v129
	v_exp_f32_e32 v122, v122
	v_exp_f32_e32 v126, v126
	v_exp_f32_e32 v123, v123
	v_exp_f32_e32 v127, v127
	v_exp_f32_e32 v124, v124
	v_exp_f32_e32 v128, v128
	v_exp_f32_e32 v125, v125
	v_exp_f32_e32 v129, v129
	v_add_f32_e32 v122, 1.0, v122
	v_add_f32_e32 v126, 1.0, v126
	v_add_f32_e32 v123, 1.0, v123
	v_add_f32_e32 v127, 1.0, v127
	v_add_f32_e32 v149, 1.0, v124
	v_add_f32_e32 v128, 1.0, v128
	v_add_f32_e32 v171, 1.0, v125
	v_add_f32_e32 v129, 1.0, v129
	v_rcp_f32_e32 v122, v122
	v_rcp_f32_e32 v124, v126
	v_rcp_f32_e32 v123, v123
	v_rcp_f32_e32 v125, v127
	v_rcp_f32_e32 v126, v149
	v_rcp_f32_e32 v128, v128
	v_rcp_f32_e32 v127, v171
	v_rcp_f32_e32 v129, v129
	v_pk_mul_f32 v[122:123], v[122:123], s[30:31] op_sel_hi:[1,0]
	v_pk_mul_f32 v[124:125], v[124:125], s[30:31] op_sel_hi:[1,0]
	v_pk_mul_f32 v[126:127], v[126:127], s[30:31] op_sel_hi:[1,0]
	v_pk_mul_f32 v[128:129], v[128:129], s[30:31] op_sel_hi:[1,0]
	v_cvt_pk_bf16_f32 v122, v122, v123
	v_cvt_pk_bf16_f32 v123, v126, v127
	v_cvt_pk_bf16_f32 v124, v124, v125
	v_cvt_pk_bf16_f32 v125, v128, v129
	global_store_dwordx4 v[180:181], v[122:125], off
	s_nop 1
	v_mov_b64_e32 v[122:123], v[208:209]
	v_mov_b64_e32 v[124:125], v[210:211]
	v_mov_b64_e32 v[126:127], v[212:213]
	v_mov_b64_e32 v[128:129], v[214:215]
	v_add_f32_e32 v118, v118, v122
	v_add_f32_e32 v114, v114, v126
	v_add_f32_e32 v119, v119, v123
	v_add_f32_e32 v115, v115, v127
	v_add_f32_e32 v120, v120, v124
	v_add_f32_e32 v116, v116, v128
	v_add_f32_e32 v121, v121, v125
	v_add_f32_e32 v117, v117, v129
	v_mul_f32_e32 v118, 0xbfb8aa3b, v118
	v_mul_f32_e32 v114, 0xbfb8aa3b, v114
	v_mul_f32_e32 v119, 0xbfb8aa3b, v119
	v_mul_f32_e32 v115, 0xbfb8aa3b, v115
	v_mul_f32_e32 v120, 0xbfb8aa3b, v120
	v_mul_f32_e32 v116, 0xbfb8aa3b, v116
	v_mul_f32_e32 v121, 0xbfb8aa3b, v121
	v_mul_f32_e32 v117, 0xbfb8aa3b, v117
	v_exp_f32_e32 v118, v118
	v_exp_f32_e32 v114, v114
	v_exp_f32_e32 v119, v119
	v_exp_f32_e32 v115, v115
	v_exp_f32_e32 v120, v120
	v_exp_f32_e32 v116, v116
	v_exp_f32_e32 v121, v121
	v_exp_f32_e32 v117, v117
	v_add_f32_e32 v118, 1.0, v118
	v_add_f32_e32 v122, 1.0, v114
	v_add_f32_e32 v119, 1.0, v119
	v_add_f32_e32 v123, 1.0, v115
	v_add_f32_e32 v120, 1.0, v120
	v_add_f32_e32 v124, 1.0, v116
	v_add_f32_e32 v121, 1.0, v121
	v_add_f32_e32 v125, 1.0, v117
	v_rcp_f32_e32 v114, v118
	v_rcp_f32_e32 v116, v122
	v_rcp_f32_e32 v115, v119
	v_rcp_f32_e32 v117, v123
	v_rcp_f32_e32 v118, v120
	v_rcp_f32_e32 v120, v124
	v_rcp_f32_e32 v119, v121
	v_rcp_f32_e32 v121, v125
	v_pk_mul_f32 v[114:115], v[114:115], s[30:31] op_sel_hi:[1,0]
	v_pk_mul_f32 v[116:117], v[116:117], s[30:31] op_sel_hi:[1,0]
	v_pk_mul_f32 v[118:119], v[118:119], s[30:31] op_sel_hi:[1,0]
	v_pk_mul_f32 v[120:121], v[120:121], s[30:31] op_sel_hi:[1,0]
	v_cvt_pk_bf16_f32 v114, v114, v115
	v_cvt_pk_bf16_f32 v115, v118, v119
	v_cvt_pk_bf16_f32 v116, v116, v117
	v_cvt_pk_bf16_f32 v117, v120, v121
	global_store_dwordx4 v[180:181], v[114:117], off offset:256
	s_nop 1
	v_mov_b64_e32 v[114:115], v[200:201]
	v_mov_b64_e32 v[116:117], v[202:203]
	v_mov_b64_e32 v[118:119], v[204:205]
	v_mov_b64_e32 v[120:121], v[206:207]
	v_or_b32_e32 v122, 16, v148
	v_ashrrev_i32_e32 v123, 31, v122
	v_lshlrev_b64 v[122:123], 12, v[122:123]
	v_lshl_add_u64 v[122:123], s[22:23], 0, v[122:123]
	v_lshl_add_u64 v[122:123], v[122:123], 0, v[150:151]
	v_add_f32_e32 v110, v110, v114
	v_add_f32_e32 v106, v106, v118
	v_add_f32_e32 v111, v111, v115
	v_add_f32_e32 v107, v107, v119
	v_add_f32_e32 v112, v112, v116
	v_add_f32_e32 v108, v108, v120
	v_add_f32_e32 v113, v113, v117
	v_add_f32_e32 v109, v109, v121
	v_mul_f32_e32 v110, 0xbfb8aa3b, v110
	v_mul_f32_e32 v106, 0xbfb8aa3b, v106
	v_mul_f32_e32 v111, 0xbfb8aa3b, v111
	v_mul_f32_e32 v107, 0xbfb8aa3b, v107
	v_mul_f32_e32 v112, 0xbfb8aa3b, v112
	v_mul_f32_e32 v108, 0xbfb8aa3b, v108
	v_mul_f32_e32 v113, 0xbfb8aa3b, v113
	v_mul_f32_e32 v109, 0xbfb8aa3b, v109
	v_exp_f32_e32 v110, v110
	v_exp_f32_e32 v106, v106
	v_exp_f32_e32 v111, v111
	v_exp_f32_e32 v107, v107
	v_exp_f32_e32 v112, v112
	v_exp_f32_e32 v108, v108
	v_exp_f32_e32 v113, v113
	v_exp_f32_e32 v109, v109
	v_add_f32_e32 v110, 1.0, v110
	v_add_f32_e32 v114, 1.0, v106
	v_add_f32_e32 v111, 1.0, v111
	v_add_f32_e32 v115, 1.0, v107
	v_add_f32_e32 v112, 1.0, v112
; __device__ __forceinline__ float sigmoidf_(float z) { return __builtin_amdgcn_rcpf(1.f + __builtin_amdgcn_exp2f(-LOG2E_ * z)); }
; #define EPI_LOOP_END asm volatile("" ::: "memory"); } }
; __device__ __forceinline__ u32x4 pack8(const f32x4 a, const f32x4 b) { u32x4 w; w.x = pk2(a[0], a[1]); w.y = pk2(a[2], a[3]); w.z = pk2(b[0], b[1]); w.w = pk2(b[2], b[3]); return w; }
;     __device__ __forceinline__ bf16_t* u(int n) const { return (bf16_t*)(ws + WS_ARENA + (size_t)n * UNIT); }
;     __device__ __forceinline__ void operator()(const f32x4 (&acc)[2][2][4][2], const Unit& u, int wr, int wc, int fr, int fq) const {
;         EPI_LOOP_BEGIN
;             const f32x4 b0 = *(const f32x4*)(bias + col), b1 = *(const f32x4*)(bias + col + 4); f32x4 a, b;
; #pragma unroll
;             for (int j = 0; j < 4; ++j) { a[j] = sigmoidf_(v0[j] + b0[j]); b[j] = sigmoidf_(v1[j] + b1[j]); if (MODE == 0) { a[j] *= -0.6065306597126334f; b[j] *= -0.6065306597126334f; } }
;             *(u32x4*)(O + (size_t)row * DM + col) = pack8(a, b);
;         EPI_LOOP_END
	v_add_f32_e32 v116, 1.0, v108
	v_add_f32_e32 v113, 1.0, v113
	v_add_f32_e32 v117, 1.0, v109
	v_rcp_f32_e32 v106, v110
	v_rcp_f32_e32 v108, v114
	v_rcp_f32_e32 v107, v111
	v_rcp_f32_e32 v109, v115
	v_rcp_f32_e32 v110, v112
	v_rcp_f32_e32 v112, v116
	v_rcp_f32_e32 v111, v113
	v_rcp_f32_e32 v113, v117
	v_pk_mul_f32 v[106:107], v[106:107], s[30:31] op_sel_hi:[1,0]
	v_pk_mul_f32 v[108:109], v[108:109], s[30:31] op_sel_hi:[1,0]
	v_pk_mul_f32 v[110:111], v[110:111], s[30:31] op_sel_hi:[1,0]
	v_pk_mul_f32 v[112:113], v[112:113], s[30:31] op_sel_hi:[1,0]
	v_cvt_pk_bf16_f32 v106, v106, v107
	v_cvt_pk_bf16_f32 v107, v110, v111
	v_cvt_pk_bf16_f32 v108, v108, v109
	v_cvt_pk_bf16_f32 v109, v112, v113
	global_store_dwordx4 v[122:123], v[106:109], off
	s_nop 1
	v_mov_b64_e32 v[106:107], v[208:209]
	v_mov_b64_e32 v[108:109], v[210:211]
	v_mov_b64_e32 v[110:111], v[212:213]
	v_mov_b64_e32 v[112:113], v[214:215]
	v_add_f32_e32 v102, v102, v106
	v_add_f32_e32 v98, v98, v110
	v_add_f32_e32 v103, v103, v107
	v_add_f32_e32 v99, v99, v111
	v_add_f32_e32 v104, v104, v108
	v_add_f32_e32 v100, v100, v112
	v_add_f32_e32 v105, v105, v109
	v_add_f32_e32 v101, v101, v113
	v_mul_f32_e32 v102, 0xbfb8aa3b, v102
	v_mul_f32_e32 v98, 0xbfb8aa3b, v98
	v_mul_f32_e32 v103, 0xbfb8aa3b, v103
	v_mul_f32_e32 v99, 0xbfb8aa3b, v99
	v_mul_f32_e32 v104, 0xbfb8aa3b, v104
	v_mul_f32_e32 v100, 0xbfb8aa3b, v100
	v_mul_f32_e32 v105, 0xbfb8aa3b, v105
	v_mul_f32_e32 v101, 0xbfb8aa3b, v101
	v_exp_f32_e32 v102, v102
	v_exp_f32_e32 v98, v98
	v_exp_f32_e32 v103, v103
	v_exp_f32_e32 v99, v99
	v_exp_f32_e32 v104, v104
	v_exp_f32_e32 v100, v100
	v_exp_f32_e32 v105, v105
	v_exp_f32_e32 v101, v101
	v_add_f32_e32 v102, 1.0, v102
	v_add_f32_e32 v106, 1.0, v98
	v_add_f32_e32 v103, 1.0, v103
	v_add_f32_e32 v107, 1.0, v99
	v_add_f32_e32 v104, 1.0, v104
	v_add_f32_e32 v108, 1.0, v100
	v_add_f32_e32 v105, 1.0, v105
	v_add_f32_e32 v109, 1.0, v101
	v_rcp_f32_e32 v98, v102
	v_rcp_f32_e32 v100, v106
	v_rcp_f32_e32 v99, v103
	v_rcp_f32_e32 v101, v107
	v_rcp_f32_e32 v102, v104
	v_rcp_f32_e32 v104, v108
	v_rcp_f32_e32 v103, v105
	v_rcp_f32_e32 v105, v109
	v_pk_mul_f32 v[98:99], v[98:99], s[30:31] op_sel_hi:[1,0]
	v_pk_mul_f32 v[100:101], v[100:101], s[30:31] op_sel_hi:[1,0]
	v_pk_mul_f32 v[102:103], v[102:103], s[30:31] op_sel_hi:[1,0]
	v_pk_mul_f32 v[104:105], v[104:105], s[30:31] op_sel_hi:[1,0]
	v_cvt_pk_bf16_f32 v98, v98, v99
	v_cvt_pk_bf16_f32 v99, v102, v103
	v_cvt_pk_bf16_f32 v100, v100, v101
	v_cvt_pk_bf16_f32 v101, v104, v105
	global_store_dwordx4 v[122:123], v[98:101], off offset:256
	s_nop 1
	v_mov_b64_e32 v[98:99], v[200:201]
	v_mov_b64_e32 v[100:101], v[202:203]
	v_mov_b64_e32 v[102:103], v[204:205]
	v_mov_b64_e32 v[104:105], v[206:207]
	v_or_b32_e32 v106, 32, v148
	v_ashrrev_i32_e32 v107, 31, v106
	v_lshlrev_b64 v[106:107], 12, v[106:107]
	v_lshl_add_u64 v[106:107], s[22:23], 0, v[106:107]
	v_lshl_add_u64 v[106:107], v[106:107], 0, v[150:151]
	v_add_f32_e32 v94, v94, v98
	v_add_f32_e32 v90, v90, v102
	v_add_f32_e32 v95, v95, v99
	v_add_f32_e32 v91, v91, v103
	v_add_f32_e32 v96, v96, v100
	v_add_f32_e32 v92, v92, v104
	v_add_f32_e32 v97, v97, v101
	v_add_f32_e32 v93, v93, v105
	v_mul_f32_e32 v94, 0xbfb8aa3b, v94
	v_mul_f32_e32 v90, 0xbfb8aa3b, v90
	v_mul_f32_e32 v95, 0xbfb8aa3b, v95
	v_mul_f32_e32 v91, 0xbfb8aa3b, v91
	v_mul_f32_e32 v96, 0xbfb8aa3b, v96
	v_mul_f32_e32 v92, 0xbfb8aa3b, v92
	v_mul_f32_e32 v97, 0xbfb8aa3b, v97
	v_mul_f32_e32 v93, 0xbfb8aa3b, v93
	v_exp_f32_e32 v94, v94
	v_exp_f32_e32 v90, v90
	v_exp_f32_e32 v95, v95
	v_exp_f32_e32 v91, v91
	v_exp_f32_e32 v96, v96
	v_exp_f32_e32 v92, v92
	v_exp_f32_e32 v97, v97
	v_exp_f32_e32 v93, v93
	v_add_f32_e32 v94, 1.0, v94
	v_add_f32_e32 v98, 1.0, v90
	v_add_f32_e32 v95, 1.0, v95
	v_add_f32_e32 v99, 1.0, v91
	v_add_f32_e32 v96, 1.0, v96
	v_add_f32_e32 v100, 1.0, v92
	v_add_f32_e32 v97, 1.0, v97
	v_add_f32_e32 v101, 1.0, v93
	v_rcp_f32_e32 v90, v94
	v_rcp_f32_e32 v92, v98
	v_rcp_f32_e32 v91, v95
	v_rcp_f32_e32 v93, v99
	v_rcp_f32_e32 v94, v96
	v_rcp_f32_e32 v96, v100
	v_rcp_f32_e32 v95, v97
	v_rcp_f32_e32 v97, v101
	v_pk_mul_f32 v[90:91], v[90:91], s[30:31] op_sel_hi:[1,0]
	v_pk_mul_f32 v[92:93], v[92:93], s[30:31] op_sel_hi:[1,0]
	v_pk_mul_f32 v[94:95], v[94:95], s[30:31] op_sel_hi:[1,0]
	v_pk_mul_f32 v[96:97], v[96:97], s[30:31] op_sel_hi:[1,0]
	v_cvt_pk_bf16_f32 v90, v90, v91
	v_cvt_pk_bf16_f32 v91, v94, v95
	v_cvt_pk_bf16_f32 v92, v92, v93
	v_cvt_pk_bf16_f32 v93, v96, v97
	global_store_dwordx4 v[106:107], v[90:93], off
	s_nop 1
	v_mov_b64_e32 v[90:91], v[208:209]
	v_mov_b64_e32 v[92:93], v[210:211]
	v_mov_b64_e32 v[94:95], v[212:213]
	v_mov_b64_e32 v[96:97], v[214:215]
	v_add_f32_e32 v86, v86, v90
	v_add_f32_e32 v82, v82, v94
	v_add_f32_e32 v87, v87, v91
	v_add_f32_e32 v83, v83, v95
	v_add_f32_e32 v88, v88, v92
	v_add_f32_e32 v84, v84, v96
	v_add_f32_e32 v89, v89, v93
	v_add_f32_e32 v85, v85, v97
	v_mul_f32_e32 v86, 0xbfb8aa3b, v86
	v_mul_f32_e32 v82, 0xbfb8aa3b, v82
	v_mul_f32_e32 v87, 0xbfb8aa3b, v87
	v_mul_f32_e32 v83, 0xbfb8aa3b, v83
	v_mul_f32_e32 v88, 0xbfb8aa3b, v88
	v_mul_f32_e32 v84, 0xbfb8aa3b, v84
	v_mul_f32_e32 v89, 0xbfb8aa3b, v89
	v_mul_f32_e32 v85, 0xbfb8aa3b, v85
	v_exp_f32_e32 v86, v86
	v_exp_f32_e32 v82, v82
	v_exp_f32_e32 v87, v87
	v_exp_f32_e32 v83, v83
	v_exp_f32_e32 v88, v88
	v_exp_f32_e32 v84, v84
	v_exp_f32_e32 v89, v89
	v_exp_f32_e32 v85, v85
	v_add_f32_e32 v86, 1.0, v86
	v_add_f32_e32 v90, 1.0, v82
	v_add_f32_e32 v87, 1.0, v87
	v_add_f32_e32 v91, 1.0, v83
	v_add_f32_e32 v88, 1.0, v88
	v_add_f32_e32 v92, 1.0, v84
	v_add_f32_e32 v89, 1.0, v89
	v_add_f32_e32 v93, 1.0, v85
	v_rcp_f32_e32 v82, v86
	v_rcp_f32_e32 v84, v90
; __device__ __forceinline__ float sigmoidf_(float z) { return __builtin_amdgcn_rcpf(1.f + __builtin_amdgcn_exp2f(-LOG2E_ * z)); }
; #define EPI_LOOP_END asm volatile("" ::: "memory"); } }
; __device__ __forceinline__ u32x4 pack8(const f32x4 a, const f32x4 b) { u32x4 w; w.x = pk2(a[0], a[1]); w.y = pk2(a[2], a[3]); w.z = pk2(b[0], b[1]); w.w = pk2(b[2], b[3]); return w; }
;     __device__ __forceinline__ bf16_t* u(int n) const { return (bf16_t*)(ws + WS_ARENA + (size_t)n * UNIT); }
;     __device__ __forceinline__ void operator()(const f32x4 (&acc)[2][2][4][2], const Unit& u, int wr, int wc, int fr, int fq) const {
;         EPI_LOOP_BEGIN
;             const f32x4 b0 = *(const f32x4*)(bias + col), b1 = *(const f32x4*)(bias + col + 4); f32x4 a, b;
; #pragma unroll
;             for (int j = 0; j < 4; ++j) { a[j] = sigmoidf_(v0[j] + b0[j]); b[j] = sigmoidf_(v1[j] + b1[j]); if (MODE == 0) { a[j] *= -0.6065306597126334f; b[j] *= -0.6065306597126334f; } }
;             *(u32x4*)(O + (size_t)row * DM + col) = pack8(a, b);
;         EPI_LOOP_END
	v_rcp_f32_e32 v83, v87
	v_rcp_f32_e32 v85, v91
	v_rcp_f32_e32 v86, v88
	v_rcp_f32_e32 v88, v92
	v_rcp_f32_e32 v87, v89
	v_rcp_f32_e32 v89, v93
	v_pk_mul_f32 v[82:83], v[82:83], s[30:31] op_sel_hi:[1,0]
	v_pk_mul_f32 v[84:85], v[84:85], s[30:31] op_sel_hi:[1,0]
	v_pk_mul_f32 v[86:87], v[86:87], s[30:31] op_sel_hi:[1,0]
	v_pk_mul_f32 v[88:89], v[88:89], s[30:31] op_sel_hi:[1,0]
	v_cvt_pk_bf16_f32 v82, v82, v83
	v_cvt_pk_bf16_f32 v83, v86, v87
	v_cvt_pk_bf16_f32 v84, v84, v85
	v_cvt_pk_bf16_f32 v85, v88, v89
	global_store_dwordx4 v[106:107], v[82:85], off offset:256
	s_nop 1
	v_mov_b64_e32 v[82:83], v[200:201]
	v_mov_b64_e32 v[84:85], v[202:203]
	v_mov_b64_e32 v[86:87], v[204:205]
	v_mov_b64_e32 v[88:89], v[206:207]
	v_or_b32_e32 v90, 48, v148
	v_ashrrev_i32_e32 v91, 31, v90
	v_lshlrev_b64 v[90:91], 12, v[90:91]
	v_lshl_add_u64 v[90:91], s[22:23], 0, v[90:91]
	v_lshl_add_u64 v[90:91], v[90:91], 0, v[150:151]
	v_add_f32_e32 v78, v78, v82
	v_add_f32_e32 v74, v74, v86
	v_add_f32_e32 v79, v79, v83
	v_add_f32_e32 v75, v75, v87
	v_add_f32_e32 v80, v80, v84
	v_add_f32_e32 v76, v76, v88
	v_add_f32_e32 v81, v81, v85
	v_add_f32_e32 v77, v77, v89
	v_mul_f32_e32 v78, 0xbfb8aa3b, v78
	v_mul_f32_e32 v74, 0xbfb8aa3b, v74
	v_mul_f32_e32 v79, 0xbfb8aa3b, v79
	v_mul_f32_e32 v75, 0xbfb8aa3b, v75
	v_mul_f32_e32 v80, 0xbfb8aa3b, v80
	v_mul_f32_e32 v76, 0xbfb8aa3b, v76
	v_mul_f32_e32 v81, 0xbfb8aa3b, v81
	v_mul_f32_e32 v77, 0xbfb8aa3b, v77
	v_exp_f32_e32 v78, v78
	v_exp_f32_e32 v74, v74
	v_exp_f32_e32 v79, v79
	v_exp_f32_e32 v75, v75
	v_exp_f32_e32 v80, v80
	v_exp_f32_e32 v76, v76
	v_exp_f32_e32 v81, v81
	v_exp_f32_e32 v77, v77
	v_add_f32_e32 v78, 1.0, v78
	v_add_f32_e32 v82, 1.0, v74
	v_add_f32_e32 v79, 1.0, v79
	v_add_f32_e32 v83, 1.0, v75
	v_add_f32_e32 v80, 1.0, v80
	v_add_f32_e32 v84, 1.0, v76
	v_add_f32_e32 v81, 1.0, v81
	v_add_f32_e32 v85, 1.0, v77
	v_rcp_f32_e32 v74, v78
	v_rcp_f32_e32 v76, v82
	v_rcp_f32_e32 v75, v79
	v_rcp_f32_e32 v77, v83
	v_rcp_f32_e32 v78, v80
	v_rcp_f32_e32 v80, v84
	v_rcp_f32_e32 v79, v81
	v_rcp_f32_e32 v81, v85
	v_pk_mul_f32 v[74:75], v[74:75], s[30:31] op_sel_hi:[1,0]
	v_pk_mul_f32 v[76:77], v[76:77], s[30:31] op_sel_hi:[1,0]
	v_pk_mul_f32 v[78:79], v[78:79], s[30:31] op_sel_hi:[1,0]
	v_pk_mul_f32 v[80:81], v[80:81], s[30:31] op_sel_hi:[1,0]
	v_cvt_pk_bf16_f32 v74, v74, v75
	v_cvt_pk_bf16_f32 v75, v78, v79
	v_cvt_pk_bf16_f32 v76, v76, v77
	v_cvt_pk_bf16_f32 v77, v80, v81
	global_store_dwordx4 v[90:91], v[74:77], off
	s_nop 1
	v_mov_b64_e32 v[74:75], v[208:209]
	v_mov_b64_e32 v[76:77], v[210:211]
	v_mov_b64_e32 v[78:79], v[212:213]
	v_mov_b64_e32 v[80:81], v[214:215]
	v_add_f32_e32 v70, v70, v74
	v_add_f32_e32 v66, v66, v78
	v_add_f32_e32 v71, v71, v75
	v_add_f32_e32 v67, v67, v79
	v_add_f32_e32 v72, v72, v76
	v_add_f32_e32 v68, v68, v80
	v_add_f32_e32 v73, v73, v77
	v_add_f32_e32 v69, v69, v81
	v_mul_f32_e32 v70, 0xbfb8aa3b, v70
	v_mul_f32_e32 v66, 0xbfb8aa3b, v66
	v_mul_f32_e32 v71, 0xbfb8aa3b, v71
	v_mul_f32_e32 v67, 0xbfb8aa3b, v67
	v_mul_f32_e32 v72, 0xbfb8aa3b, v72
	v_mul_f32_e32 v68, 0xbfb8aa3b, v68
	v_mul_f32_e32 v73, 0xbfb8aa3b, v73
	v_mul_f32_e32 v69, 0xbfb8aa3b, v69
	v_exp_f32_e32 v70, v70
	v_exp_f32_e32 v66, v66
	v_exp_f32_e32 v71, v71
	v_exp_f32_e32 v67, v67
	v_exp_f32_e32 v72, v72
	v_exp_f32_e32 v68, v68
	v_exp_f32_e32 v73, v73
	v_exp_f32_e32 v69, v69
	v_add_f32_e32 v70, 1.0, v70
	v_add_f32_e32 v74, 1.0, v66
	v_add_f32_e32 v71, 1.0, v71
	v_add_f32_e32 v75, 1.0, v67
	v_add_f32_e32 v72, 1.0, v72
	v_add_f32_e32 v76, 1.0, v68
	v_add_f32_e32 v73, 1.0, v73
	v_add_f32_e32 v77, 1.0, v69
	v_rcp_f32_e32 v66, v70
	v_rcp_f32_e32 v68, v74
	v_rcp_f32_e32 v67, v71
	v_rcp_f32_e32 v69, v75
	v_rcp_f32_e32 v70, v72
	v_rcp_f32_e32 v72, v76
	v_rcp_f32_e32 v71, v73
	v_rcp_f32_e32 v73, v77
	v_pk_mul_f32 v[66:67], v[66:67], s[30:31] op_sel_hi:[1,0]
	v_pk_mul_f32 v[68:69], v[68:69], s[30:31] op_sel_hi:[1,0]
	v_pk_mul_f32 v[70:71], v[70:71], s[30:31] op_sel_hi:[1,0]
	v_pk_mul_f32 v[72:73], v[72:73], s[30:31] op_sel_hi:[1,0]
	v_cvt_pk_bf16_f32 v66, v66, v67
	v_cvt_pk_bf16_f32 v67, v70, v71
	v_cvt_pk_bf16_f32 v68, v68, v69
	v_cvt_pk_bf16_f32 v69, v72, v73
	global_store_dwordx4 v[90:91], v[66:69], off offset:256
	s_nop 1
	v_mov_b64_e32 v[66:67], v[200:201]
	v_mov_b64_e32 v[68:69], v[202:203]
	v_mov_b64_e32 v[70:71], v[204:205]
	v_mov_b64_e32 v[72:73], v[206:207]
	v_add_u32_e32 v74, 0x80, v148
	v_ashrrev_i32_e32 v75, 31, v74
	v_lshlrev_b64 v[74:75], 12, v[74:75]
	v_lshl_add_u64 v[74:75], s[22:23], 0, v[74:75]
	v_lshl_add_u64 v[74:75], v[74:75], 0, v[150:151]
	v_add_f32_e32 v62, v62, v66
	v_add_f32_e32 v58, v58, v70
	v_add_f32_e32 v63, v63, v67
	v_add_f32_e32 v59, v59, v71
	v_add_f32_e32 v64, v64, v68
	v_add_f32_e32 v60, v60, v72
	v_add_f32_e32 v65, v65, v69
	v_add_f32_e32 v61, v61, v73
	v_mul_f32_e32 v62, 0xbfb8aa3b, v62
	v_mul_f32_e32 v58, 0xbfb8aa3b, v58
	v_mul_f32_e32 v63, 0xbfb8aa3b, v63
	v_mul_f32_e32 v59, 0xbfb8aa3b, v59
	v_mul_f32_e32 v64, 0xbfb8aa3b, v64
	v_mul_f32_e32 v60, 0xbfb8aa3b, v60
	v_mul_f32_e32 v65, 0xbfb8aa3b, v65
	v_mul_f32_e32 v61, 0xbfb8aa3b, v61
	v_exp_f32_e32 v62, v62
	v_exp_f32_e32 v58, v58
	v_exp_f32_e32 v63, v63
	v_exp_f32_e32 v59, v59
	v_exp_f32_e32 v64, v64
	v_exp_f32_e32 v60, v60
	v_exp_f32_e32 v65, v65
	v_exp_f32_e32 v61, v61
	v_add_f32_e32 v62, 1.0, v62
	v_add_f32_e32 v66, 1.0, v58
	v_add_f32_e32 v63, 1.0, v63
	v_add_f32_e32 v67, 1.0, v59
	v_add_f32_e32 v64, 1.0, v64
	v_add_f32_e32 v68, 1.0, v60
	v_add_f32_e32 v65, 1.0, v65
	v_add_f32_e32 v69, 1.0, v61
	v_rcp_f32_e32 v58, v62
	v_rcp_f32_e32 v60, v66
	v_rcp_f32_e32 v59, v63
	v_rcp_f32_e32 v61, v67
	v_rcp_f32_e32 v62, v64
	v_rcp_f32_e32 v64, v68
	v_rcp_f32_e32 v63, v65
; __device__ __forceinline__ float sigmoidf_(float z) { return __builtin_amdgcn_rcpf(1.f + __builtin_amdgcn_exp2f(-LOG2E_ * z)); }
; #define EPI_LOOP_END asm volatile("" ::: "memory"); } }
; __device__ __forceinline__ u32x4 pack8(const f32x4 a, const f32x4 b) { u32x4 w; w.x = pk2(a[0], a[1]); w.y = pk2(a[2], a[3]); w.z = pk2(b[0], b[1]); w.w = pk2(b[2], b[3]); return w; }
;     __device__ __forceinline__ bf16_t* u(int n) const { return (bf16_t*)(ws + WS_ARENA + (size_t)n * UNIT); }
;     __device__ __forceinline__ void operator()(const f32x4 (&acc)[2][2][4][2], const Unit& u, int wr, int wc, int fr, int fq) const {
;         EPI_LOOP_BEGIN
;             const f32x4 b0 = *(const f32x4*)(bias + col), b1 = *(const f32x4*)(bias + col + 4); f32x4 a, b;
; #pragma unroll
;             for (int j = 0; j < 4; ++j) { a[j] = sigmoidf_(v0[j] + b0[j]); b[j] = sigmoidf_(v1[j] + b1[j]); if (MODE == 0) { a[j] *= -0.6065306597126334f; b[j] *= -0.6065306597126334f; } }
;             *(u32x4*)(O + (size_t)row * DM + col) = pack8(a, b);
;         EPI_LOOP_END
	v_rcp_f32_e32 v65, v69
	v_pk_mul_f32 v[58:59], v[58:59], s[30:31] op_sel_hi:[1,0]
	v_pk_mul_f32 v[60:61], v[60:61], s[30:31] op_sel_hi:[1,0]
	v_pk_mul_f32 v[62:63], v[62:63], s[30:31] op_sel_hi:[1,0]
	v_pk_mul_f32 v[64:65], v[64:65], s[30:31] op_sel_hi:[1,0]
	v_cvt_pk_bf16_f32 v58, v58, v59
	v_cvt_pk_bf16_f32 v59, v62, v63
	v_cvt_pk_bf16_f32 v60, v60, v61
	v_cvt_pk_bf16_f32 v61, v64, v65
	global_store_dwordx4 v[74:75], v[58:61], off
	s_nop 1
	v_mov_b64_e32 v[58:59], v[208:209]
	v_mov_b64_e32 v[60:61], v[210:211]
	v_mov_b64_e32 v[62:63], v[212:213]
	v_mov_b64_e32 v[64:65], v[214:215]
	v_add_f32_e32 v54, v54, v58
	v_add_f32_e32 v50, v50, v62
	v_add_f32_e32 v55, v55, v59
	v_add_f32_e32 v51, v51, v63
	v_add_f32_e32 v56, v56, v60
	v_add_f32_e32 v52, v52, v64
	v_add_f32_e32 v57, v57, v61
	v_add_f32_e32 v53, v53, v65
	v_mul_f32_e32 v54, 0xbfb8aa3b, v54
	v_mul_f32_e32 v50, 0xbfb8aa3b, v50
	v_mul_f32_e32 v55, 0xbfb8aa3b, v55
	v_mul_f32_e32 v51, 0xbfb8aa3b, v51
	v_mul_f32_e32 v56, 0xbfb8aa3b, v56
	v_mul_f32_e32 v52, 0xbfb8aa3b, v52
	v_mul_f32_e32 v57, 0xbfb8aa3b, v57
	v_mul_f32_e32 v53, 0xbfb8aa3b, v53
	v_exp_f32_e32 v54, v54
	v_exp_f32_e32 v50, v50
	v_exp_f32_e32 v55, v55
	v_exp_f32_e32 v51, v51
	v_exp_f32_e32 v56, v56
	v_exp_f32_e32 v52, v52
	v_exp_f32_e32 v57, v57
	v_exp_f32_e32 v53, v53
	v_add_f32_e32 v54, 1.0, v54
	v_add_f32_e32 v58, 1.0, v50
	v_add_f32_e32 v55, 1.0, v55
	v_add_f32_e32 v59, 1.0, v51
	v_add_f32_e32 v56, 1.0, v56
	v_add_f32_e32 v60, 1.0, v52
	v_add_f32_e32 v57, 1.0, v57
	v_add_f32_e32 v61, 1.0, v53
	v_rcp_f32_e32 v50, v54
	v_rcp_f32_e32 v52, v58
	v_rcp_f32_e32 v51, v55
	v_rcp_f32_e32 v53, v59
	v_rcp_f32_e32 v54, v56
	v_rcp_f32_e32 v56, v60
	v_rcp_f32_e32 v55, v57
	v_rcp_f32_e32 v57, v61
	v_pk_mul_f32 v[50:51], v[50:51], s[30:31] op_sel_hi:[1,0]
	v_pk_mul_f32 v[52:53], v[52:53], s[30:31] op_sel_hi:[1,0]
	v_pk_mul_f32 v[54:55], v[54:55], s[30:31] op_sel_hi:[1,0]
	v_pk_mul_f32 v[56:57], v[56:57], s[30:31] op_sel_hi:[1,0]
	v_cvt_pk_bf16_f32 v50, v50, v51
	v_cvt_pk_bf16_f32 v51, v54, v55
	v_cvt_pk_bf16_f32 v52, v52, v53
	v_cvt_pk_bf16_f32 v53, v56, v57
	global_store_dwordx4 v[74:75], v[50:53], off offset:256
	s_nop 1
	v_mov_b64_e32 v[50:51], v[200:201]
	v_mov_b64_e32 v[52:53], v[202:203]
	v_mov_b64_e32 v[54:55], v[204:205]
	v_mov_b64_e32 v[56:57], v[206:207]
	v_add_u32_e32 v58, 0x90, v148
	v_ashrrev_i32_e32 v59, 31, v58
	v_lshlrev_b64 v[58:59], 12, v[58:59]
	v_lshl_add_u64 v[58:59], s[22:23], 0, v[58:59]
	v_lshl_add_u64 v[58:59], v[58:59], 0, v[150:151]
	v_add_f32_e32 v46, v46, v50
	v_add_f32_e32 v42, v42, v54
	v_add_f32_e32 v47, v47, v51
	v_add_f32_e32 v43, v43, v55
	v_add_f32_e32 v48, v48, v52
	v_add_f32_e32 v44, v44, v56
	v_add_f32_e32 v49, v49, v53
	v_add_f32_e32 v45, v45, v57
	v_mul_f32_e32 v46, 0xbfb8aa3b, v46
	v_mul_f32_e32 v42, 0xbfb8aa3b, v42
	v_mul_f32_e32 v47, 0xbfb8aa3b, v47
	v_mul_f32_e32 v43, 0xbfb8aa3b, v43
	v_mul_f32_e32 v48, 0xbfb8aa3b, v48
	v_mul_f32_e32 v44, 0xbfb8aa3b, v44
	v_mul_f32_e32 v49, 0xbfb8aa3b, v49
	v_mul_f32_e32 v45, 0xbfb8aa3b, v45
	v_exp_f32_e32 v46, v46
	v_exp_f32_e32 v42, v42
	v_exp_f32_e32 v47, v47
	v_exp_f32_e32 v43, v43
	v_exp_f32_e32 v48, v48
	v_exp_f32_e32 v44, v44
	v_exp_f32_e32 v49, v49
	v_exp_f32_e32 v45, v45
	v_add_f32_e32 v46, 1.0, v46
	v_add_f32_e32 v50, 1.0, v42
	v_add_f32_e32 v47, 1.0, v47
	v_add_f32_e32 v51, 1.0, v43
	v_add_f32_e32 v48, 1.0, v48
	v_add_f32_e32 v52, 1.0, v44
	v_add_f32_e32 v49, 1.0, v49
	v_add_f32_e32 v53, 1.0, v45
	v_rcp_f32_e32 v42, v46
	v_rcp_f32_e32 v44, v50
	v_rcp_f32_e32 v43, v47
	v_rcp_f32_e32 v45, v51
	v_rcp_f32_e32 v46, v48
	v_rcp_f32_e32 v48, v52
	v_rcp_f32_e32 v47, v49
	v_rcp_f32_e32 v49, v53
	v_pk_mul_f32 v[42:43], v[42:43], s[30:31] op_sel_hi:[1,0]
	v_pk_mul_f32 v[44:45], v[44:45], s[30:31] op_sel_hi:[1,0]
	v_pk_mul_f32 v[46:47], v[46:47], s[30:31] op_sel_hi:[1,0]
	v_pk_mul_f32 v[48:49], v[48:49], s[30:31] op_sel_hi:[1,0]
	v_cvt_pk_bf16_f32 v42, v42, v43
	v_cvt_pk_bf16_f32 v43, v46, v47
	v_cvt_pk_bf16_f32 v44, v44, v45
	v_cvt_pk_bf16_f32 v45, v48, v49
	global_store_dwordx4 v[58:59], v[42:45], off
	s_nop 1
	v_mov_b64_e32 v[42:43], v[208:209]
	v_mov_b64_e32 v[44:45], v[210:211]
	v_mov_b64_e32 v[46:47], v[212:213]
	v_mov_b64_e32 v[48:49], v[214:215]
	v_add_f32_e32 v38, v38, v42
	v_add_f32_e32 v34, v34, v46
	v_add_f32_e32 v39, v39, v43
	v_add_f32_e32 v35, v35, v47
	v_add_f32_e32 v40, v40, v44
	v_add_f32_e32 v36, v36, v48
	v_add_f32_e32 v41, v41, v45
	v_add_f32_e32 v37, v37, v49
	v_mul_f32_e32 v38, 0xbfb8aa3b, v38
	v_mul_f32_e32 v34, 0xbfb8aa3b, v34
	v_mul_f32_e32 v39, 0xbfb8aa3b, v39
	v_mul_f32_e32 v35, 0xbfb8aa3b, v35
	v_mul_f32_e32 v40, 0xbfb8aa3b, v40
	v_mul_f32_e32 v36, 0xbfb8aa3b, v36
	v_mul_f32_e32 v41, 0xbfb8aa3b, v41
	v_mul_f32_e32 v37, 0xbfb8aa3b, v37
	v_exp_f32_e32 v38, v38
	v_exp_f32_e32 v34, v34
	v_exp_f32_e32 v39, v39
	v_exp_f32_e32 v35, v35
	v_exp_f32_e32 v40, v40
	v_exp_f32_e32 v36, v36
	v_exp_f32_e32 v41, v41
	v_exp_f32_e32 v37, v37
	v_add_f32_e32 v38, 1.0, v38
	v_add_f32_e32 v42, 1.0, v34
	v_add_f32_e32 v39, 1.0, v39
	v_add_f32_e32 v43, 1.0, v35
	v_add_f32_e32 v40, 1.0, v40
	v_add_f32_e32 v44, 1.0, v36
	v_add_f32_e32 v41, 1.0, v41
	v_add_f32_e32 v45, 1.0, v37
	v_rcp_f32_e32 v34, v38
	v_rcp_f32_e32 v36, v42
	v_rcp_f32_e32 v35, v39
	v_rcp_f32_e32 v37, v43
	v_rcp_f32_e32 v38, v40
	v_rcp_f32_e32 v40, v44
	v_rcp_f32_e32 v39, v41
	v_rcp_f32_e32 v41, v45
	v_pk_mul_f32 v[34:35], v[34:35], s[30:31] op_sel_hi:[1,0]
	v_pk_mul_f32 v[36:37], v[36:37], s[30:31] op_sel_hi:[1,0]
	v_pk_mul_f32 v[38:39], v[38:39], s[30:31] op_sel_hi:[1,0]
	v_pk_mul_f32 v[40:41], v[40:41], s[30:31] op_sel_hi:[1,0]
	v_cvt_pk_bf16_f32 v34, v34, v35
	v_cvt_pk_bf16_f32 v35, v38, v39
; __device__ __forceinline__ float sigmoidf_(float z) { return __builtin_amdgcn_rcpf(1.f + __builtin_amdgcn_exp2f(-LOG2E_ * z)); }
; #define EPI_LOOP_END asm volatile("" ::: "memory"); } }
; __device__ __forceinline__ u32x4 pack8(const f32x4 a, const f32x4 b) { u32x4 w; w.x = pk2(a[0], a[1]); w.y = pk2(a[2], a[3]); w.z = pk2(b[0], b[1]); w.w = pk2(b[2], b[3]); return w; }
;     __device__ __forceinline__ bf16_t* u(int n) const { return (bf16_t*)(ws + WS_ARENA + (size_t)n * UNIT); }
;     __device__ __forceinline__ void operator()(const f32x4 (&acc)[2][2][4][2], const Unit& u, int wr, int wc, int fr, int fq) const {
;         EPI_LOOP_BEGIN
;             const f32x4 b0 = *(const f32x4*)(bias + col), b1 = *(const f32x4*)(bias + col + 4); f32x4 a, b;
; #pragma unroll
;             for (int j = 0; j < 4; ++j) { a[j] = sigmoidf_(v0[j] + b0[j]); b[j] = sigmoidf_(v1[j] + b1[j]); if (MODE == 0) { a[j] *= -0.6065306597126334f; b[j] *= -0.6065306597126334f; } }
;             *(u32x4*)(O + (size_t)row * DM + col) = pack8(a, b);
;         EPI_LOOP_END
	v_cvt_pk_bf16_f32 v36, v36, v37
	v_cvt_pk_bf16_f32 v37, v40, v41
	global_store_dwordx4 v[58:59], v[34:37], off offset:256
	s_nop 1
	v_mov_b64_e32 v[34:35], v[200:201]
	v_mov_b64_e32 v[36:37], v[202:203]
	v_mov_b64_e32 v[38:39], v[204:205]
	v_mov_b64_e32 v[40:41], v[206:207]
	v_add_u32_e32 v42, 0xa0, v148
	v_ashrrev_i32_e32 v43, 31, v42
	v_lshlrev_b64 v[42:43], 12, v[42:43]
	v_lshl_add_u64 v[42:43], s[22:23], 0, v[42:43]
	v_lshl_add_u64 v[42:43], v[42:43], 0, v[150:151]
	v_add_f32_e32 v30, v30, v34
	v_add_f32_e32 v26, v26, v38
	v_add_f32_e32 v31, v31, v35
	v_add_f32_e32 v27, v27, v39
	v_add_f32_e32 v32, v32, v36
	v_add_f32_e32 v28, v28, v40
	v_add_f32_e32 v33, v33, v37
	v_add_f32_e32 v29, v29, v41
	v_mul_f32_e32 v30, 0xbfb8aa3b, v30
	v_mul_f32_e32 v26, 0xbfb8aa3b, v26
	v_mul_f32_e32 v31, 0xbfb8aa3b, v31
	v_mul_f32_e32 v27, 0xbfb8aa3b, v27
	v_mul_f32_e32 v32, 0xbfb8aa3b, v32
	v_mul_f32_e32 v28, 0xbfb8aa3b, v28
	v_mul_f32_e32 v33, 0xbfb8aa3b, v33
	v_mul_f32_e32 v29, 0xbfb8aa3b, v29
	v_exp_f32_e32 v30, v30
	v_exp_f32_e32 v26, v26
	v_exp_f32_e32 v31, v31
	v_exp_f32_e32 v27, v27
	v_exp_f32_e32 v32, v32
	v_exp_f32_e32 v28, v28
	v_exp_f32_e32 v33, v33
	v_exp_f32_e32 v29, v29
	v_add_f32_e32 v30, 1.0, v30
	v_add_f32_e32 v34, 1.0, v26
	v_add_f32_e32 v31, 1.0, v31
	v_add_f32_e32 v35, 1.0, v27
	v_add_f32_e32 v32, 1.0, v32
	v_add_f32_e32 v36, 1.0, v28
	v_add_f32_e32 v33, 1.0, v33
	v_add_f32_e32 v37, 1.0, v29
	v_rcp_f32_e32 v26, v30
	v_rcp_f32_e32 v28, v34
	v_rcp_f32_e32 v27, v31
	v_rcp_f32_e32 v29, v35
	v_rcp_f32_e32 v30, v32
	v_rcp_f32_e32 v32, v36
	v_rcp_f32_e32 v31, v33
	v_rcp_f32_e32 v33, v37
	v_pk_mul_f32 v[26:27], v[26:27], s[30:31] op_sel_hi:[1,0]
	v_pk_mul_f32 v[28:29], v[28:29], s[30:31] op_sel_hi:[1,0]
	v_pk_mul_f32 v[30:31], v[30:31], s[30:31] op_sel_hi:[1,0]
	v_pk_mul_f32 v[32:33], v[32:33], s[30:31] op_sel_hi:[1,0]
	v_cvt_pk_bf16_f32 v26, v26, v27
	v_cvt_pk_bf16_f32 v27, v30, v31
	v_cvt_pk_bf16_f32 v28, v28, v29
	v_cvt_pk_bf16_f32 v29, v32, v33
	global_store_dwordx4 v[42:43], v[26:29], off
	s_nop 1
	v_mov_b64_e32 v[26:27], v[208:209]
	v_mov_b64_e32 v[28:29], v[210:211]
	v_mov_b64_e32 v[30:31], v[212:213]
	v_mov_b64_e32 v[32:33], v[214:215]
	v_add_f32_e32 v22, v22, v26
	v_add_f32_e32 v18, v18, v30
	v_add_f32_e32 v23, v23, v27
	v_add_f32_e32 v19, v19, v31
	v_add_f32_e32 v24, v24, v28
	v_add_f32_e32 v20, v20, v32
	v_add_f32_e32 v25, v25, v29
	v_add_f32_e32 v21, v21, v33
	v_mul_f32_e32 v22, 0xbfb8aa3b, v22
	v_mul_f32_e32 v18, 0xbfb8aa3b, v18
	v_mul_f32_e32 v23, 0xbfb8aa3b, v23
	v_mul_f32_e32 v19, 0xbfb8aa3b, v19
	v_mul_f32_e32 v24, 0xbfb8aa3b, v24
	v_mul_f32_e32 v20, 0xbfb8aa3b, v20
	v_mul_f32_e32 v25, 0xbfb8aa3b, v25
	v_mul_f32_e32 v21, 0xbfb8aa3b, v21
	v_exp_f32_e32 v22, v22
	v_exp_f32_e32 v18, v18
	v_exp_f32_e32 v23, v23
	v_exp_f32_e32 v19, v19
	v_exp_f32_e32 v24, v24
	v_exp_f32_e32 v20, v20
	v_exp_f32_e32 v25, v25
	v_exp_f32_e32 v21, v21
	v_add_f32_e32 v22, 1.0, v22
	v_add_f32_e32 v26, 1.0, v18
	v_add_f32_e32 v23, 1.0, v23
	v_add_f32_e32 v27, 1.0, v19
	v_add_f32_e32 v24, 1.0, v24
	v_add_f32_e32 v28, 1.0, v20
	v_add_f32_e32 v25, 1.0, v25
	v_add_f32_e32 v29, 1.0, v21
	v_rcp_f32_e32 v18, v22
	v_rcp_f32_e32 v20, v26
	v_rcp_f32_e32 v19, v23
	v_rcp_f32_e32 v21, v27
	v_rcp_f32_e32 v22, v24
	v_rcp_f32_e32 v24, v28
	v_rcp_f32_e32 v23, v25
	v_rcp_f32_e32 v25, v29
	v_pk_mul_f32 v[18:19], v[18:19], s[30:31] op_sel_hi:[1,0]
	v_pk_mul_f32 v[20:21], v[20:21], s[30:31] op_sel_hi:[1,0]
	v_pk_mul_f32 v[22:23], v[22:23], s[30:31] op_sel_hi:[1,0]
	v_pk_mul_f32 v[24:25], v[24:25], s[30:31] op_sel_hi:[1,0]
	v_cvt_pk_bf16_f32 v18, v18, v19
	v_cvt_pk_bf16_f32 v19, v22, v23
	v_cvt_pk_bf16_f32 v20, v20, v21
	v_cvt_pk_bf16_f32 v21, v24, v25
; #define PG8_BAR __builtin_amdgcn_s_barrier()
; __device__ __forceinline__ float sigmoidf_(float z) { return __builtin_amdgcn_rcpf(1.f + __builtin_amdgcn_exp2f(-LOG2E_ * z)); }
; #define EPI_LOOP_END asm volatile("" ::: "memory"); } }
; __device__ __forceinline__ u32x4 pack8(const f32x4 a, const f32x4 b) { u32x4 w; w.x = pk2(a[0], a[1]); w.y = pk2(a[2], a[3]); w.z = pk2(b[0], b[1]); w.w = pk2(b[2], b[3]); return w; }
;     __device__ __forceinline__ bf16_t* u(int n) const { return (bf16_t*)(ws + WS_ARENA + (size_t)n * UNIT); }
; template <class Epi, class Sched, bool ALIGN_EPI = false, bool SP2 = false>
; __device__ __forceinline__ void gemm_phase(PG8_LAS unsigned char* lds, const Gemm g, const Sched& S, const Epi& E) {
;     ...
;         if constexpr (ALIGN_EPI) { if (wr == 0) PG8_BAR; }
;         if constexpr (!Epi::AFTER_DRAIN) { E(acc, cur, wr, wc, fr, fq); S.done(cur); }
;         if (!has_next) break;
; #pragma unroll
;         for (int a = 0; a < 2; ++a)
; #pragma unroll
;             for (int b = 0; b < 2; ++b)
; #pragma unroll
;                 for (int m = 0; m < 4; ++m)
; #pragma unroll
;                     for (int n = 0; n < 2; ++n) acc[a][b][m][n] = (f32x4){0.f, 0.f, 0.f, 0.f};
;         cur = nxt; cA = nA; cB = nB; ++ui;
;         if constexpr (ALIGN_EPI) { if (wr == 1) PG8_BAR; }
;     __device__ __forceinline__ void operator()(const f32x4 (&acc)[2][2][4][2], const Unit& u, int wr, int wc, int fr, int fq) const {
;         EPI_LOOP_BEGIN
;             const f32x4 b0 = *(const f32x4*)(bias + col), b1 = *(const f32x4*)(bias + col + 4); f32x4 a, b;
; #pragma unroll
;             for (int j = 0; j < 4; ++j) { a[j] = sigmoidf_(v0[j] + b0[j]); b[j] = sigmoidf_(v1[j] + b1[j]); if (MODE == 0) { a[j] *= -0.6065306597126334f; b[j] *= -0.6065306597126334f; } }
;             *(u32x4*)(O + (size_t)row * DM + col) = pack8(a, b);
;         EPI_LOOP_END
	global_store_dwordx4 v[42:43], v[18:21], off offset:256
	s_nop 1
	v_mov_b64_e32 v[18:19], v[200:201]
	v_mov_b64_e32 v[20:21], v[202:203]
	v_mov_b64_e32 v[22:23], v[204:205]
	v_mov_b64_e32 v[24:25], v[206:207]
	v_add_u32_e32 v26, 0xb0, v148
	v_ashrrev_i32_e32 v27, 31, v26
	v_lshlrev_b64 v[26:27], 12, v[26:27]
	v_lshl_add_u64 v[26:27], s[22:23], 0, v[26:27]
	v_lshl_add_u64 v[26:27], v[26:27], 0, v[150:151]
	v_add_f32_e32 v14, v14, v18
	v_add_f32_e32 v10, v10, v22
	v_add_f32_e32 v15, v15, v19
	v_add_f32_e32 v11, v11, v23
	v_add_f32_e32 v16, v16, v20
	v_add_f32_e32 v12, v12, v24
	v_add_f32_e32 v17, v17, v21
	v_add_f32_e32 v13, v13, v25
	v_mul_f32_e32 v14, 0xbfb8aa3b, v14
	v_mul_f32_e32 v10, 0xbfb8aa3b, v10
	v_mul_f32_e32 v15, 0xbfb8aa3b, v15
	v_mul_f32_e32 v11, 0xbfb8aa3b, v11
	v_mul_f32_e32 v16, 0xbfb8aa3b, v16
	v_mul_f32_e32 v12, 0xbfb8aa3b, v12
	v_mul_f32_e32 v17, 0xbfb8aa3b, v17
	v_mul_f32_e32 v13, 0xbfb8aa3b, v13
	v_exp_f32_e32 v14, v14
	v_exp_f32_e32 v10, v10
	v_exp_f32_e32 v15, v15
	v_exp_f32_e32 v11, v11
	v_exp_f32_e32 v16, v16
	v_exp_f32_e32 v12, v12
	v_exp_f32_e32 v17, v17
	v_exp_f32_e32 v13, v13
	v_add_f32_e32 v14, 1.0, v14
	v_add_f32_e32 v18, 1.0, v10
	v_add_f32_e32 v15, 1.0, v15
	v_add_f32_e32 v19, 1.0, v11
	v_add_f32_e32 v16, 1.0, v16
	v_add_f32_e32 v20, 1.0, v12
	v_add_f32_e32 v17, 1.0, v17
	v_add_f32_e32 v21, 1.0, v13
	v_rcp_f32_e32 v10, v14
	v_rcp_f32_e32 v12, v18
	v_rcp_f32_e32 v11, v15
	v_rcp_f32_e32 v13, v19
	v_rcp_f32_e32 v14, v16
	v_rcp_f32_e32 v16, v20
	v_rcp_f32_e32 v15, v17
	v_rcp_f32_e32 v17, v21
	v_pk_mul_f32 v[10:11], v[10:11], s[30:31] op_sel_hi:[1,0]
	v_pk_mul_f32 v[12:13], v[12:13], s[30:31] op_sel_hi:[1,0]
	v_pk_mul_f32 v[14:15], v[14:15], s[30:31] op_sel_hi:[1,0]
	v_pk_mul_f32 v[16:17], v[16:17], s[30:31] op_sel_hi:[1,0]
	v_cvt_pk_bf16_f32 v10, v10, v11
	v_cvt_pk_bf16_f32 v11, v14, v15
	v_cvt_pk_bf16_f32 v12, v12, v13
	v_cvt_pk_bf16_f32 v13, v16, v17
	global_store_dwordx4 v[26:27], v[10:13], off
	s_nop 1
	v_mov_b64_e32 v[10:11], v[208:209]
	v_mov_b64_e32 v[12:13], v[210:211]
	v_mov_b64_e32 v[14:15], v[212:213]
	v_mov_b64_e32 v[16:17], v[214:215]
	v_add_f32_e32 v6, v6, v10
	v_add_f32_e32 v2, v2, v14
	v_add_f32_e32 v7, v7, v11
	v_add_f32_e32 v3, v3, v15
	v_add_f32_e32 v8, v8, v12
	v_add_f32_e32 v4, v4, v16
	v_add_f32_e32 v9, v9, v13
	v_add_f32_e32 v5, v5, v17
	v_mul_f32_e32 v6, 0xbfb8aa3b, v6
	v_mul_f32_e32 v2, 0xbfb8aa3b, v2
	v_mul_f32_e32 v7, 0xbfb8aa3b, v7
	v_mul_f32_e32 v3, 0xbfb8aa3b, v3
	v_mul_f32_e32 v8, 0xbfb8aa3b, v8
	v_mul_f32_e32 v4, 0xbfb8aa3b, v4
	v_mul_f32_e32 v9, 0xbfb8aa3b, v9
	v_mul_f32_e32 v5, 0xbfb8aa3b, v5
	v_exp_f32_e32 v6, v6
	v_exp_f32_e32 v2, v2
	v_exp_f32_e32 v7, v7
	v_exp_f32_e32 v3, v3
	v_exp_f32_e32 v8, v8
	v_exp_f32_e32 v4, v4
	v_exp_f32_e32 v9, v9
	v_exp_f32_e32 v5, v5
	v_add_f32_e32 v6, 1.0, v6
	v_add_f32_e32 v10, 1.0, v2
	v_add_f32_e32 v7, 1.0, v7
	v_add_f32_e32 v11, 1.0, v3
	v_add_f32_e32 v8, 1.0, v8
	v_add_f32_e32 v12, 1.0, v4
	v_add_f32_e32 v9, 1.0, v9
	v_add_f32_e32 v13, 1.0, v5
	v_rcp_f32_e32 v2, v6
	v_rcp_f32_e32 v4, v10
	v_rcp_f32_e32 v3, v7
	v_rcp_f32_e32 v5, v11
	v_rcp_f32_e32 v6, v8
	v_rcp_f32_e32 v8, v12
	v_rcp_f32_e32 v7, v9
	v_rcp_f32_e32 v9, v13
	v_pk_mul_f32 v[2:3], v[2:3], s[30:31] op_sel_hi:[1,0]
	v_pk_mul_f32 v[4:5], v[4:5], s[30:31] op_sel_hi:[1,0]
	v_pk_mul_f32 v[6:7], v[6:7], s[30:31] op_sel_hi:[1,0]
	v_pk_mul_f32 v[8:9], v[8:9], s[30:31] op_sel_hi:[1,0]
	v_cvt_pk_bf16_f32 v2, v2, v3
	v_cvt_pk_bf16_f32 v3, v6, v7
	v_cvt_pk_bf16_f32 v4, v4, v5
	v_cvt_pk_bf16_f32 v5, v8, v9
	global_store_dwordx4 v[26:27], v[2:5], off offset:256
	s_cbranch_vccnz .LBB0_1505
	s_andn2_b64 vcc, exec, s[20:21]
	s_cbranch_vccnz .LBB0_1504
	s_barrier
	s_branch .LBB0_1504

; __device__ __forceinline__ float sigmoidf_(float z) { return __builtin_amdgcn_rcpf(1.f + __builtin_amdgcn_exp2f(-LOG2E_ * z)); }
; #define EPI_LOOP_END asm volatile("" ::: "memory"); } }
; __device__ __forceinline__ u32x4 pack8(const f32x4 a, const f32x4 b) { u32x4 w; w.x = pk2(a[0], a[1]); w.y = pk2(a[2], a[3]); w.z = pk2(b[0], b[1]); w.w = pk2(b[2], b[3]); return w; }
;     __device__ __forceinline__ bf16_t* u(int n) const { return (bf16_t*)(ws + WS_ARENA + (size_t)n * UNIT); }
;     __device__ __forceinline__ void operator()(const f32x4 (&acc)[2][2][4][2], const Unit& u, int wr, int wc, int fr, int fq) const {
;         EPI_LOOP_BEGIN
;             const f32x4 b0 = *(const f32x4*)(bias + col), b1 = *(const f32x4*)(bias + col + 4); f32x4 a, b;
; #pragma unroll
;             for (int j = 0; j < 4; ++j) { a[j] = sigmoidf_(v0[j] + b0[j]); b[j] = sigmoidf_(v1[j] + b1[j]); if (MODE == 0) { a[j] *= -0.6065306597126334f; b[j] *= -0.6065306597126334f; } }
;             *(u32x4*)(O + (size_t)row * DM + col) = pack8(a, b);
;         EPI_LOOP_END
.LBB0_1551:
	v_lshl_or_b32 v150, s55, 8, v155
	v_ashrrev_i32_e32 v151, 31, v150
	v_lshl_add_u64 v[146:147], v[150:151], 2, s[16:17]
	global_load_dwordx4 v[200:203], v[146:147], off
	global_load_dwordx4 v[204:207], v[146:147], off offset:16
	global_load_dwordx4 v[208:211], v[146:147], off offset:512
	global_load_dwordx4 v[212:215], v[146:147], off offset:528
	v_lshl_add_u32 v148, s54, 8, v160
	v_ashrrev_i32_e32 v149, 31, v148
	v_lshlrev_b64 v[158:159], 12, v[148:149]
	v_lshlrev_b64 v[150:151], 1, v[150:151]
	v_lshl_add_u64 v[158:159], s[18:19], 0, v[158:159]
	v_lshl_add_u64 v[158:159], v[158:159], 0, v[150:151]
	s_and_b64 vcc, exec, s[0:1]
	s_mov_b64 s[0:1], -1
	s_waitcnt vmcnt(0)
	v_mov_b64_e32 v[162:163], v[200:201]
	v_mov_b64_e32 v[164:165], v[202:203]
	v_mov_b64_e32 v[166:167], v[204:205]
	v_mov_b64_e32 v[168:169], v[206:207]
	v_add_f32_e32 v122, v122, v162
	v_add_f32_e32 v126, v126, v166
	v_add_f32_e32 v123, v123, v163
	v_add_f32_e32 v127, v127, v167
	v_add_f32_e32 v124, v124, v164
	v_add_f32_e32 v128, v128, v168
	v_add_f32_e32 v125, v125, v165
	v_add_f32_e32 v129, v129, v169
	v_mul_f32_e32 v122, 0xbfb8aa3b, v122
	v_mul_f32_e32 v126, 0xbfb8aa3b, v126
	v_mul_f32_e32 v123, 0xbfb8aa3b, v123
	v_mul_f32_e32 v127, 0xbfb8aa3b, v127
	v_mul_f32_e32 v124, 0xbfb8aa3b, v124
	v_mul_f32_e32 v128, 0xbfb8aa3b, v128
	v_mul_f32_e32 v125, 0xbfb8aa3b, v125
	v_mul_f32_e32 v129, 0xbfb8aa3b, v129
	v_exp_f32_e32 v122, v122
	v_exp_f32_e32 v126, v126
	v_exp_f32_e32 v123, v123
	v_exp_f32_e32 v127, v127
	v_exp_f32_e32 v124, v124
	v_exp_f32_e32 v128, v128
	v_exp_f32_e32 v125, v125
	v_exp_f32_e32 v129, v129
	v_add_f32_e32 v122, 1.0, v122
	v_add_f32_e32 v126, 1.0, v126
	v_add_f32_e32 v123, 1.0, v123
	v_add_f32_e32 v127, 1.0, v127
	v_add_f32_e32 v124, 1.0, v124
	v_add_f32_e32 v128, 1.0, v128
	v_add_f32_e32 v125, 1.0, v125
	v_add_f32_e32 v129, 1.0, v129
	v_rcp_f32_e32 v122, v122
	v_rcp_f32_e32 v126, v126
	v_rcp_f32_e32 v123, v123
	v_rcp_f32_e32 v127, v127
	v_rcp_f32_e32 v124, v124
	v_rcp_f32_e32 v125, v125
	v_rcp_f32_e32 v128, v128
	v_rcp_f32_e32 v129, v129
	v_cvt_pk_bf16_f32 v122, v122, v123
	v_cvt_pk_bf16_f32 v123, v124, v125
	v_cvt_pk_bf16_f32 v124, v126, v127
	v_cvt_pk_bf16_f32 v125, v128, v129
	global_store_dwordx4 v[158:159], v[122:125], off
	s_nop 1
	v_mov_b64_e32 v[122:123], v[208:209]
	v_mov_b64_e32 v[124:125], v[210:211]
	v_mov_b64_e32 v[126:127], v[212:213]
	v_mov_b64_e32 v[128:129], v[214:215]
	v_add_f32_e32 v118, v118, v122
	v_add_f32_e32 v114, v114, v126
	v_add_f32_e32 v119, v119, v123
	v_add_f32_e32 v115, v115, v127
	v_add_f32_e32 v120, v120, v124
	v_add_f32_e32 v116, v116, v128
	v_add_f32_e32 v121, v121, v125
	v_add_f32_e32 v117, v117, v129
	v_mul_f32_e32 v118, 0xbfb8aa3b, v118
	v_mul_f32_e32 v114, 0xbfb8aa3b, v114
	v_mul_f32_e32 v119, 0xbfb8aa3b, v119
	v_mul_f32_e32 v115, 0xbfb8aa3b, v115
	v_mul_f32_e32 v120, 0xbfb8aa3b, v120
	v_mul_f32_e32 v116, 0xbfb8aa3b, v116
	v_mul_f32_e32 v121, 0xbfb8aa3b, v121
	v_mul_f32_e32 v117, 0xbfb8aa3b, v117
	v_exp_f32_e32 v118, v118
	v_exp_f32_e32 v114, v114
	v_exp_f32_e32 v119, v119
	v_exp_f32_e32 v115, v115
	v_exp_f32_e32 v120, v120
	v_exp_f32_e32 v116, v116
	v_exp_f32_e32 v121, v121
	v_exp_f32_e32 v117, v117
	v_add_f32_e32 v118, 1.0, v118
	v_add_f32_e32 v114, 1.0, v114
	v_add_f32_e32 v119, 1.0, v119
	v_add_f32_e32 v115, 1.0, v115
	v_add_f32_e32 v120, 1.0, v120
	v_add_f32_e32 v116, 1.0, v116
	v_add_f32_e32 v121, 1.0, v121
	v_add_f32_e32 v117, 1.0, v117
	v_rcp_f32_e32 v118, v118
	v_rcp_f32_e32 v122, v114
	v_rcp_f32_e32 v114, v119
	v_rcp_f32_e32 v119, v115
	v_rcp_f32_e32 v115, v120
	v_rcp_f32_e32 v120, v121
	v_rcp_f32_e32 v121, v116
	v_rcp_f32_e32 v117, v117
	v_cvt_pk_bf16_f32 v114, v118, v114
	v_cvt_pk_bf16_f32 v115, v115, v120
	v_cvt_pk_bf16_f32 v116, v122, v119
	v_cvt_pk_bf16_f32 v117, v121, v117
	global_store_dwordx4 v[158:159], v[114:117], off offset:256
	s_nop 1
	v_mov_b64_e32 v[114:115], v[200:201]
	v_mov_b64_e32 v[116:117], v[202:203]
	v_mov_b64_e32 v[118:119], v[204:205]
	v_mov_b64_e32 v[120:121], v[206:207]
	v_or_b32_e32 v122, 16, v148
	v_ashrrev_i32_e32 v123, 31, v122
	v_lshlrev_b64 v[122:123], 12, v[122:123]
	v_lshl_add_u64 v[122:123], s[18:19], 0, v[122:123]
	v_lshl_add_u64 v[122:123], v[122:123], 0, v[150:151]
	v_add_f32_e32 v110, v110, v114
	v_add_f32_e32 v106, v106, v118
	v_add_f32_e32 v111, v111, v115
	v_add_f32_e32 v107, v107, v119
	v_add_f32_e32 v112, v112, v116
	v_add_f32_e32 v108, v108, v120
	v_add_f32_e32 v113, v113, v117
	v_add_f32_e32 v109, v109, v121
	v_mul_f32_e32 v110, 0xbfb8aa3b, v110
	v_mul_f32_e32 v106, 0xbfb8aa3b, v106
	v_mul_f32_e32 v111, 0xbfb8aa3b, v111
	v_mul_f32_e32 v107, 0xbfb8aa3b, v107
	v_mul_f32_e32 v112, 0xbfb8aa3b, v112
	v_mul_f32_e32 v108, 0xbfb8aa3b, v108
	v_mul_f32_e32 v113, 0xbfb8aa3b, v113
	v_mul_f32_e32 v109, 0xbfb8aa3b, v109
	v_exp_f32_e32 v110, v110
	v_exp_f32_e32 v106, v106
	v_exp_f32_e32 v111, v111
	v_exp_f32_e32 v107, v107
	v_exp_f32_e32 v112, v112
	v_exp_f32_e32 v108, v108
	v_exp_f32_e32 v113, v113
	v_exp_f32_e32 v109, v109
	v_add_f32_e32 v110, 1.0, v110
	v_add_f32_e32 v106, 1.0, v106
	v_add_f32_e32 v111, 1.0, v111
	v_add_f32_e32 v107, 1.0, v107
	v_add_f32_e32 v112, 1.0, v112
	v_add_f32_e32 v108, 1.0, v108
	v_add_f32_e32 v113, 1.0, v113
	v_add_f32_e32 v109, 1.0, v109
	v_rcp_f32_e32 v110, v110
	v_rcp_f32_e32 v114, v106
	v_rcp_f32_e32 v106, v111
	v_rcp_f32_e32 v111, v107
	v_rcp_f32_e32 v107, v112
	v_rcp_f32_e32 v112, v113
	v_rcp_f32_e32 v113, v108
	v_rcp_f32_e32 v109, v109
	v_cvt_pk_bf16_f32 v106, v110, v106
	v_cvt_pk_bf16_f32 v107, v107, v112
	v_cvt_pk_bf16_f32 v108, v114, v111
	v_cvt_pk_bf16_f32 v109, v113, v109
	global_store_dwordx4 v[122:123], v[106:109], off
; __device__ __forceinline__ float sigmoidf_(float z) { return __builtin_amdgcn_rcpf(1.f + __builtin_amdgcn_exp2f(-LOG2E_ * z)); }
; #define EPI_LOOP_END asm volatile("" ::: "memory"); } }
; __device__ __forceinline__ u32x4 pack8(const f32x4 a, const f32x4 b) { u32x4 w; w.x = pk2(a[0], a[1]); w.y = pk2(a[2], a[3]); w.z = pk2(b[0], b[1]); w.w = pk2(b[2], b[3]); return w; }
;     __device__ __forceinline__ void operator()(const f32x4 (&acc)[2][2][4][2], const Unit& u, int wr, int wc, int fr, int fq) const {
;         EPI_LOOP_BEGIN
;             const f32x4 b0 = *(const f32x4*)(bias + col), b1 = *(const f32x4*)(bias + col + 4); f32x4 a, b;
; #pragma unroll
;             for (int j = 0; j < 4; ++j) { a[j] = sigmoidf_(v0[j] + b0[j]); b[j] = sigmoidf_(v1[j] + b1[j]); if (MODE == 0) { a[j] *= -0.6065306597126334f; b[j] *= -0.6065306597126334f; } }
;             *(u32x4*)(O + (size_t)row * DM + col) = pack8(a, b);
;         EPI_LOOP_END
	s_nop 1
	v_mov_b64_e32 v[106:107], v[208:209]
	v_mov_b64_e32 v[108:109], v[210:211]
	v_mov_b64_e32 v[110:111], v[212:213]
	v_mov_b64_e32 v[112:113], v[214:215]
	v_add_f32_e32 v102, v102, v106
	v_add_f32_e32 v98, v98, v110
	v_add_f32_e32 v103, v103, v107
	v_add_f32_e32 v99, v99, v111
	v_add_f32_e32 v104, v104, v108
	v_add_f32_e32 v100, v100, v112
	v_add_f32_e32 v105, v105, v109
	v_add_f32_e32 v101, v101, v113
	v_mul_f32_e32 v102, 0xbfb8aa3b, v102
	v_mul_f32_e32 v98, 0xbfb8aa3b, v98
	v_mul_f32_e32 v103, 0xbfb8aa3b, v103
	v_mul_f32_e32 v99, 0xbfb8aa3b, v99
	v_mul_f32_e32 v104, 0xbfb8aa3b, v104
	v_mul_f32_e32 v100, 0xbfb8aa3b, v100
	v_mul_f32_e32 v105, 0xbfb8aa3b, v105
	v_mul_f32_e32 v101, 0xbfb8aa3b, v101
	v_exp_f32_e32 v102, v102
	v_exp_f32_e32 v98, v98
	v_exp_f32_e32 v103, v103
	v_exp_f32_e32 v99, v99
	v_exp_f32_e32 v104, v104
	v_exp_f32_e32 v100, v100
	v_exp_f32_e32 v105, v105
	v_exp_f32_e32 v101, v101
	v_add_f32_e32 v102, 1.0, v102
	v_add_f32_e32 v98, 1.0, v98
	v_add_f32_e32 v103, 1.0, v103
	v_add_f32_e32 v99, 1.0, v99
	v_add_f32_e32 v104, 1.0, v104
	v_add_f32_e32 v100, 1.0, v100
	v_add_f32_e32 v105, 1.0, v105
	v_add_f32_e32 v101, 1.0, v101
	v_rcp_f32_e32 v102, v102
	v_rcp_f32_e32 v106, v98
	v_rcp_f32_e32 v98, v103
	v_rcp_f32_e32 v103, v99
	v_rcp_f32_e32 v99, v104
	v_rcp_f32_e32 v104, v105
	v_rcp_f32_e32 v105, v100
	v_rcp_f32_e32 v101, v101
	v_cvt_pk_bf16_f32 v98, v102, v98
	v_cvt_pk_bf16_f32 v99, v99, v104
	v_cvt_pk_bf16_f32 v100, v106, v103
	v_cvt_pk_bf16_f32 v101, v105, v101
	global_store_dwordx4 v[122:123], v[98:101], off offset:256
	s_nop 1
	v_mov_b64_e32 v[98:99], v[200:201]
	v_mov_b64_e32 v[100:101], v[202:203]
	v_mov_b64_e32 v[102:103], v[204:205]
	v_mov_b64_e32 v[104:105], v[206:207]
	v_or_b32_e32 v106, 32, v148
	v_ashrrev_i32_e32 v107, 31, v106
	v_lshlrev_b64 v[106:107], 12, v[106:107]
	v_lshl_add_u64 v[106:107], s[18:19], 0, v[106:107]
	v_lshl_add_u64 v[106:107], v[106:107], 0, v[150:151]
	v_add_f32_e32 v94, v94, v98
	v_add_f32_e32 v90, v90, v102
	v_add_f32_e32 v95, v95, v99
	v_add_f32_e32 v91, v91, v103
	v_add_f32_e32 v96, v96, v100
	v_add_f32_e32 v92, v92, v104
	v_add_f32_e32 v97, v97, v101
	v_add_f32_e32 v93, v93, v105
	v_mul_f32_e32 v94, 0xbfb8aa3b, v94
	v_mul_f32_e32 v90, 0xbfb8aa3b, v90
	v_mul_f32_e32 v95, 0xbfb8aa3b, v95
	v_mul_f32_e32 v91, 0xbfb8aa3b, v91
	v_mul_f32_e32 v96, 0xbfb8aa3b, v96
	v_mul_f32_e32 v92, 0xbfb8aa3b, v92
	v_mul_f32_e32 v97, 0xbfb8aa3b, v97
	v_mul_f32_e32 v93, 0xbfb8aa3b, v93
	v_exp_f32_e32 v94, v94
	v_exp_f32_e32 v90, v90
	v_exp_f32_e32 v95, v95
	v_exp_f32_e32 v91, v91
	v_exp_f32_e32 v96, v96
	v_exp_f32_e32 v92, v92
	v_exp_f32_e32 v97, v97
	v_exp_f32_e32 v93, v93
	v_add_f32_e32 v94, 1.0, v94
	v_add_f32_e32 v90, 1.0, v90
	v_add_f32_e32 v95, 1.0, v95
	v_add_f32_e32 v91, 1.0, v91
	v_add_f32_e32 v96, 1.0, v96
	v_add_f32_e32 v92, 1.0, v92
	v_add_f32_e32 v97, 1.0, v97
	v_add_f32_e32 v93, 1.0, v93
	v_rcp_f32_e32 v94, v94
	v_rcp_f32_e32 v98, v90
	v_rcp_f32_e32 v90, v95
	v_rcp_f32_e32 v95, v91
	v_rcp_f32_e32 v91, v96
	v_rcp_f32_e32 v96, v97
	v_rcp_f32_e32 v97, v92
	v_rcp_f32_e32 v93, v93
	v_cvt_pk_bf16_f32 v90, v94, v90
	v_cvt_pk_bf16_f32 v91, v91, v96
	v_cvt_pk_bf16_f32 v92, v98, v95
	v_cvt_pk_bf16_f32 v93, v97, v93
	global_store_dwordx4 v[106:107], v[90:93], off
	s_nop 1
	v_mov_b64_e32 v[90:91], v[208:209]
	v_mov_b64_e32 v[92:93], v[210:211]
	v_mov_b64_e32 v[94:95], v[212:213]
	v_mov_b64_e32 v[96:97], v[214:215]
	v_add_f32_e32 v86, v86, v90
	v_add_f32_e32 v82, v82, v94
	v_add_f32_e32 v87, v87, v91
	v_add_f32_e32 v83, v83, v95
	v_add_f32_e32 v88, v88, v92
	v_add_f32_e32 v84, v84, v96
	v_add_f32_e32 v89, v89, v93
	v_add_f32_e32 v85, v85, v97
	v_mul_f32_e32 v86, 0xbfb8aa3b, v86
	v_mul_f32_e32 v82, 0xbfb8aa3b, v82
	v_mul_f32_e32 v87, 0xbfb8aa3b, v87
	v_mul_f32_e32 v83, 0xbfb8aa3b, v83
	v_mul_f32_e32 v88, 0xbfb8aa3b, v88
	v_mul_f32_e32 v84, 0xbfb8aa3b, v84
	v_mul_f32_e32 v89, 0xbfb8aa3b, v89
	v_mul_f32_e32 v85, 0xbfb8aa3b, v85
	v_exp_f32_e32 v86, v86
	v_exp_f32_e32 v82, v82
	v_exp_f32_e32 v87, v87
	v_exp_f32_e32 v83, v83
	v_exp_f32_e32 v88, v88
	v_exp_f32_e32 v84, v84
	v_exp_f32_e32 v89, v89
	v_exp_f32_e32 v85, v85
	v_add_f32_e32 v86, 1.0, v86
	v_add_f32_e32 v82, 1.0, v82
	v_add_f32_e32 v87, 1.0, v87
	v_add_f32_e32 v83, 1.0, v83
	v_add_f32_e32 v88, 1.0, v88
	v_add_f32_e32 v84, 1.0, v84
	v_add_f32_e32 v89, 1.0, v89
	v_add_f32_e32 v85, 1.0, v85
	v_rcp_f32_e32 v86, v86
	v_rcp_f32_e32 v90, v82
	v_rcp_f32_e32 v82, v87
	v_rcp_f32_e32 v87, v83
	v_rcp_f32_e32 v83, v88
	v_rcp_f32_e32 v88, v89
	v_rcp_f32_e32 v89, v84
	v_rcp_f32_e32 v85, v85
	v_cvt_pk_bf16_f32 v82, v86, v82
	v_cvt_pk_bf16_f32 v83, v83, v88
	v_cvt_pk_bf16_f32 v84, v90, v87
	v_cvt_pk_bf16_f32 v85, v89, v85
	global_store_dwordx4 v[106:107], v[82:85], off offset:256
	s_nop 1
	v_mov_b64_e32 v[82:83], v[200:201]
	v_mov_b64_e32 v[84:85], v[202:203]
	v_mov_b64_e32 v[86:87], v[204:205]
	v_mov_b64_e32 v[88:89], v[206:207]
	v_or_b32_e32 v90, 48, v148
	v_ashrrev_i32_e32 v91, 31, v90
	v_lshlrev_b64 v[90:91], 12, v[90:91]
	v_lshl_add_u64 v[90:91], s[18:19], 0, v[90:91]
	v_lshl_add_u64 v[90:91], v[90:91], 0, v[150:151]
	v_add_f32_e32 v78, v78, v82
	v_add_f32_e32 v74, v74, v86
	v_add_f32_e32 v79, v79, v83
	v_add_f32_e32 v75, v75, v87
	v_add_f32_e32 v80, v80, v84
	v_add_f32_e32 v76, v76, v88
	v_add_f32_e32 v81, v81, v85
	v_add_f32_e32 v77, v77, v89
	v_mul_f32_e32 v78, 0xbfb8aa3b, v78
	v_mul_f32_e32 v74, 0xbfb8aa3b, v74
	v_mul_f32_e32 v79, 0xbfb8aa3b, v79
	v_mul_f32_e32 v75, 0xbfb8aa3b, v75
	v_mul_f32_e32 v80, 0xbfb8aa3b, v80
	v_mul_f32_e32 v76, 0xbfb8aa3b, v76
	v_mul_f32_e32 v81, 0xbfb8aa3b, v81
	v_mul_f32_e32 v77, 0xbfb8aa3b, v77
	v_exp_f32_e32 v78, v78
; __device__ __forceinline__ float sigmoidf_(float z) { return __builtin_amdgcn_rcpf(1.f + __builtin_amdgcn_exp2f(-LOG2E_ * z)); }
; __device__ __forceinline__ u32x4 pack8(const f32x4 a, const f32x4 b) { u32x4 w; w.x = pk2(a[0], a[1]); w.y = pk2(a[2], a[3]); w.z = pk2(b[0], b[1]); w.w = pk2(b[2], b[3]); return w; }
;     __device__ __forceinline__ void operator()(const f32x4 (&acc)[2][2][4][2], const Unit& u, int wr, int wc, int fr, int fq) const {
;     ...
;             const f32x4 b0 = *(const f32x4*)(bias + col), b1 = *(const f32x4*)(bias + col + 4); f32x4 a, b;
; #pragma unroll
;             for (int j = 0; j < 4; ++j) { a[j] = sigmoidf_(v0[j] + b0[j]); b[j] = sigmoidf_(v1[j] + b1[j]); if (MODE == 0) { a[j] *= -0.6065306597126334f; b[j] *= -0.6065306597126334f; } }
;             *(u32x4*)(O + (size_t)row * DM + col) = pack8(a, b);
	v_exp_f32_e32 v74, v74
	v_exp_f32_e32 v79, v79
	v_exp_f32_e32 v75, v75
	v_exp_f32_e32 v80, v80
	v_exp_f32_e32 v76, v76
	v_exp_f32_e32 v81, v81
	v_exp_f32_e32 v77, v77
	v_add_f32_e32 v78, 1.0, v78
	v_add_f32_e32 v74, 1.0, v74
	v_add_f32_e32 v79, 1.0, v79
	v_add_f32_e32 v75, 1.0, v75
	v_add_f32_e32 v80, 1.0, v80
	v_add_f32_e32 v76, 1.0, v76
	v_add_f32_e32 v81, 1.0, v81
	v_add_f32_e32 v77, 1.0, v77
	v_rcp_f32_e32 v78, v78
	v_rcp_f32_e32 v82, v74
	v_rcp_f32_e32 v74, v79
	v_rcp_f32_e32 v79, v75
	v_rcp_f32_e32 v75, v80
	v_rcp_f32_e32 v80, v81
	v_rcp_f32_e32 v81, v76
	v_rcp_f32_e32 v77, v77
	v_cvt_pk_bf16_f32 v74, v78, v74
	v_cvt_pk_bf16_f32 v75, v75, v80
	v_cvt_pk_bf16_f32 v76, v82, v79
	v_cvt_pk_bf16_f32 v77, v81, v77
	global_store_dwordx4 v[90:91], v[74:77], off
	s_nop 1
	v_mov_b64_e32 v[74:75], v[208:209]
	v_mov_b64_e32 v[76:77], v[210:211]
	v_mov_b64_e32 v[78:79], v[212:213]
	v_mov_b64_e32 v[80:81], v[214:215]
	v_add_f32_e32 v70, v70, v74
	v_add_f32_e32 v66, v66, v78
	v_add_f32_e32 v71, v71, v75
	v_add_f32_e32 v67, v67, v79
	v_add_f32_e32 v72, v72, v76
	v_add_f32_e32 v68, v68, v80
	v_add_f32_e32 v73, v73, v77
	v_add_f32_e32 v69, v69, v81
	v_mul_f32_e32 v70, 0xbfb8aa3b, v70
	v_mul_f32_e32 v66, 0xbfb8aa3b, v66
	v_mul_f32_e32 v71, 0xbfb8aa3b, v71
	v_mul_f32_e32 v67, 0xbfb8aa3b, v67
	v_mul_f32_e32 v72, 0xbfb8aa3b, v72
	v_mul_f32_e32 v68, 0xbfb8aa3b, v68
	v_mul_f32_e32 v73, 0xbfb8aa3b, v73
	v_mul_f32_e32 v69, 0xbfb8aa3b, v69
	v_exp_f32_e32 v70, v70
	v_exp_f32_e32 v66, v66
	v_exp_f32_e32 v71, v71
	v_exp_f32_e32 v67, v67
	v_exp_f32_e32 v72, v72
	v_exp_f32_e32 v68, v68
	v_exp_f32_e32 v73, v73
	v_exp_f32_e32 v69, v69
	v_add_f32_e32 v70, 1.0, v70
	v_add_f32_e32 v66, 1.0, v66
	v_add_f32_e32 v71, 1.0, v71
	v_add_f32_e32 v67, 1.0, v67
	v_add_f32_e32 v72, 1.0, v72
	v_add_f32_e32 v68, 1.0, v68
	v_add_f32_e32 v73, 1.0, v73
	v_add_f32_e32 v69, 1.0, v69
	v_rcp_f32_e32 v70, v70
	v_rcp_f32_e32 v74, v66
	v_rcp_f32_e32 v66, v71
	v_rcp_f32_e32 v71, v67
	v_rcp_f32_e32 v67, v72
	v_rcp_f32_e32 v72, v73
	v_rcp_f32_e32 v73, v68
	v_rcp_f32_e32 v69, v69
	v_cvt_pk_bf16_f32 v66, v70, v66
	v_cvt_pk_bf16_f32 v67, v67, v72
	v_cvt_pk_bf16_f32 v68, v74, v71
	v_cvt_pk_bf16_f32 v69, v73, v69
	global_store_dwordx4 v[90:91], v[66:69], off offset:256
	s_nop 1
	v_mov_b64_e32 v[66:67], v[200:201]
	v_mov_b64_e32 v[68:69], v[202:203]
	v_mov_b64_e32 v[70:71], v[204:205]
	v_mov_b64_e32 v[72:73], v[206:207]
	v_add_u32_e32 v74, 0x80, v148
	v_ashrrev_i32_e32 v75, 31, v74
	v_lshlrev_b64 v[74:75], 12, v[74:75]
	v_lshl_add_u64 v[74:75], s[18:19], 0, v[74:75]
	v_lshl_add_u64 v[74:75], v[74:75], 0, v[150:151]
	v_add_f32_e32 v62, v62, v66
	v_add_f32_e32 v58, v58, v70
	v_add_f32_e32 v63, v63, v67
	v_add_f32_e32 v59, v59, v71
	v_add_f32_e32 v64, v64, v68
	v_add_f32_e32 v60, v60, v72
	v_add_f32_e32 v65, v65, v69
	v_add_f32_e32 v61, v61, v73
	v_mul_f32_e32 v62, 0xbfb8aa3b, v62
	v_mul_f32_e32 v58, 0xbfb8aa3b, v58
	v_mul_f32_e32 v63, 0xbfb8aa3b, v63
	v_mul_f32_e32 v59, 0xbfb8aa3b, v59
	v_mul_f32_e32 v64, 0xbfb8aa3b, v64
	v_mul_f32_e32 v60, 0xbfb8aa3b, v60
	v_mul_f32_e32 v65, 0xbfb8aa3b, v65
	v_mul_f32_e32 v61, 0xbfb8aa3b, v61
	v_exp_f32_e32 v62, v62
	v_exp_f32_e32 v58, v58
	v_exp_f32_e32 v63, v63
	v_exp_f32_e32 v59, v59
	v_exp_f32_e32 v64, v64
	v_exp_f32_e32 v60, v60
	v_exp_f32_e32 v65, v65
	v_exp_f32_e32 v61, v61
	v_add_f32_e32 v62, 1.0, v62
	v_add_f32_e32 v58, 1.0, v58
	v_add_f32_e32 v63, 1.0, v63
	v_add_f32_e32 v59, 1.0, v59
	v_add_f32_e32 v64, 1.0, v64
	v_add_f32_e32 v60, 1.0, v60
	v_add_f32_e32 v65, 1.0, v65
	v_add_f32_e32 v61, 1.0, v61
	v_rcp_f32_e32 v62, v62
	v_rcp_f32_e32 v66, v58
	v_rcp_f32_e32 v58, v63
	v_rcp_f32_e32 v63, v59
	v_rcp_f32_e32 v59, v64
	v_rcp_f32_e32 v64, v65
	v_rcp_f32_e32 v65, v60
	v_rcp_f32_e32 v61, v61
	v_cvt_pk_bf16_f32 v58, v62, v58
	v_cvt_pk_bf16_f32 v59, v59, v64
	v_cvt_pk_bf16_f32 v60, v66, v63
	v_cvt_pk_bf16_f32 v61, v65, v61
	global_store_dwordx4 v[74:75], v[58:61], off
	s_nop 1
	v_mov_b64_e32 v[58:59], v[208:209]
	v_mov_b64_e32 v[60:61], v[210:211]
	v_mov_b64_e32 v[62:63], v[212:213]
	v_mov_b64_e32 v[64:65], v[214:215]
	v_add_f32_e32 v54, v54, v58
	v_add_f32_e32 v50, v50, v62
	v_add_f32_e32 v55, v55, v59
	v_add_f32_e32 v51, v51, v63
	v_add_f32_e32 v56, v56, v60
	v_add_f32_e32 v52, v52, v64
	v_add_f32_e32 v57, v57, v61
	v_add_f32_e32 v53, v53, v65
	v_mul_f32_e32 v54, 0xbfb8aa3b, v54
	v_mul_f32_e32 v50, 0xbfb8aa3b, v50
	v_mul_f32_e32 v55, 0xbfb8aa3b, v55
	v_mul_f32_e32 v51, 0xbfb8aa3b, v51
	v_mul_f32_e32 v56, 0xbfb8aa3b, v56
	v_mul_f32_e32 v52, 0xbfb8aa3b, v52
	v_mul_f32_e32 v57, 0xbfb8aa3b, v57
	v_mul_f32_e32 v53, 0xbfb8aa3b, v53
	v_exp_f32_e32 v54, v54
	v_exp_f32_e32 v50, v50
	v_exp_f32_e32 v55, v55
	v_exp_f32_e32 v51, v51
	v_exp_f32_e32 v56, v56
	v_exp_f32_e32 v52, v52
	v_exp_f32_e32 v57, v57
	v_exp_f32_e32 v53, v53
	v_add_f32_e32 v54, 1.0, v54
	v_add_f32_e32 v50, 1.0, v50
	v_add_f32_e32 v55, 1.0, v55
	v_add_f32_e32 v51, 1.0, v51
	v_add_f32_e32 v56, 1.0, v56
	v_add_f32_e32 v52, 1.0, v52
	v_add_f32_e32 v57, 1.0, v57
	v_add_f32_e32 v53, 1.0, v53
	v_rcp_f32_e32 v54, v54
	v_rcp_f32_e32 v58, v50
	v_rcp_f32_e32 v50, v55
	v_rcp_f32_e32 v55, v51
	v_rcp_f32_e32 v51, v56
	v_rcp_f32_e32 v56, v57
	v_rcp_f32_e32 v57, v52
	v_rcp_f32_e32 v53, v53
	v_cvt_pk_bf16_f32 v50, v54, v50
	v_cvt_pk_bf16_f32 v51, v51, v56
	v_cvt_pk_bf16_f32 v52, v58, v55
	v_cvt_pk_bf16_f32 v53, v57, v53
	global_store_dwordx4 v[74:75], v[50:53], off offset:256
	s_nop 1
	v_mov_b64_e32 v[50:51], v[200:201]
	v_mov_b64_e32 v[52:53], v[202:203]
	v_mov_b64_e32 v[54:55], v[204:205]
	v_mov_b64_e32 v[56:57], v[206:207]
	v_add_u32_e32 v58, 0x90, v148
	v_ashrrev_i32_e32 v59, 31, v58
	v_lshlrev_b64 v[58:59], 12, v[58:59]
; __device__ __forceinline__ float sigmoidf_(float z) { return __builtin_amdgcn_rcpf(1.f + __builtin_amdgcn_exp2f(-LOG2E_ * z)); }
; __device__ __forceinline__ u32x4 pack8(const f32x4 a, const f32x4 b) { u32x4 w; w.x = pk2(a[0], a[1]); w.y = pk2(a[2], a[3]); w.z = pk2(b[0], b[1]); w.w = pk2(b[2], b[3]); return w; }
;     __device__ __forceinline__ void operator()(const f32x4 (&acc)[2][2][4][2], const Unit& u, int wr, int wc, int fr, int fq) const {
;     ...
;             const f32x4 b0 = *(const f32x4*)(bias + col), b1 = *(const f32x4*)(bias + col + 4); f32x4 a, b;
; #pragma unroll
;             for (int j = 0; j < 4; ++j) { a[j] = sigmoidf_(v0[j] + b0[j]); b[j] = sigmoidf_(v1[j] + b1[j]); if (MODE == 0) { a[j] *= -0.6065306597126334f; b[j] *= -0.6065306597126334f; } }
;             *(u32x4*)(O + (size_t)row * DM + col) = pack8(a, b);
	v_lshl_add_u64 v[58:59], s[18:19], 0, v[58:59]
	v_lshl_add_u64 v[58:59], v[58:59], 0, v[150:151]
	v_add_f32_e32 v46, v46, v50
	v_add_f32_e32 v42, v42, v54
	v_add_f32_e32 v47, v47, v51
	v_add_f32_e32 v43, v43, v55
	v_add_f32_e32 v48, v48, v52
	v_add_f32_e32 v44, v44, v56
	v_add_f32_e32 v49, v49, v53
	v_add_f32_e32 v45, v45, v57
	v_mul_f32_e32 v46, 0xbfb8aa3b, v46
	v_mul_f32_e32 v42, 0xbfb8aa3b, v42
	v_mul_f32_e32 v47, 0xbfb8aa3b, v47
	v_mul_f32_e32 v43, 0xbfb8aa3b, v43
	v_mul_f32_e32 v48, 0xbfb8aa3b, v48
	v_mul_f32_e32 v44, 0xbfb8aa3b, v44
	v_mul_f32_e32 v49, 0xbfb8aa3b, v49
	v_mul_f32_e32 v45, 0xbfb8aa3b, v45
	v_exp_f32_e32 v46, v46
	v_exp_f32_e32 v42, v42
	v_exp_f32_e32 v47, v47
	v_exp_f32_e32 v43, v43
	v_exp_f32_e32 v48, v48
	v_exp_f32_e32 v44, v44
	v_exp_f32_e32 v49, v49
	v_exp_f32_e32 v45, v45
	v_add_f32_e32 v46, 1.0, v46
	v_add_f32_e32 v42, 1.0, v42
	v_add_f32_e32 v47, 1.0, v47
	v_add_f32_e32 v43, 1.0, v43
	v_add_f32_e32 v48, 1.0, v48
	v_add_f32_e32 v44, 1.0, v44
	v_add_f32_e32 v49, 1.0, v49
	v_add_f32_e32 v45, 1.0, v45
	v_rcp_f32_e32 v46, v46
	v_rcp_f32_e32 v50, v42
	v_rcp_f32_e32 v42, v47
	v_rcp_f32_e32 v47, v43
	v_rcp_f32_e32 v43, v48
	v_rcp_f32_e32 v48, v49
	v_rcp_f32_e32 v49, v44
	v_rcp_f32_e32 v45, v45
	v_cvt_pk_bf16_f32 v42, v46, v42
	v_cvt_pk_bf16_f32 v43, v43, v48
	v_cvt_pk_bf16_f32 v44, v50, v47
	v_cvt_pk_bf16_f32 v45, v49, v45
	global_store_dwordx4 v[58:59], v[42:45], off
	s_nop 1
	v_mov_b64_e32 v[42:43], v[208:209]
	v_mov_b64_e32 v[44:45], v[210:211]
	v_mov_b64_e32 v[46:47], v[212:213]
	v_mov_b64_e32 v[48:49], v[214:215]
	v_add_f32_e32 v38, v38, v42
	v_add_f32_e32 v34, v34, v46
	v_add_f32_e32 v39, v39, v43
	v_add_f32_e32 v35, v35, v47
	v_add_f32_e32 v40, v40, v44
	v_add_f32_e32 v36, v36, v48
	v_add_f32_e32 v41, v41, v45
	v_add_f32_e32 v37, v37, v49
	v_mul_f32_e32 v38, 0xbfb8aa3b, v38
	v_mul_f32_e32 v34, 0xbfb8aa3b, v34
	v_mul_f32_e32 v39, 0xbfb8aa3b, v39
	v_mul_f32_e32 v35, 0xbfb8aa3b, v35
	v_mul_f32_e32 v40, 0xbfb8aa3b, v40
	v_mul_f32_e32 v36, 0xbfb8aa3b, v36
	v_mul_f32_e32 v41, 0xbfb8aa3b, v41
	v_mul_f32_e32 v37, 0xbfb8aa3b, v37
	v_exp_f32_e32 v38, v38
	v_exp_f32_e32 v34, v34
	v_exp_f32_e32 v39, v39
	v_exp_f32_e32 v35, v35
	v_exp_f32_e32 v40, v40
	v_exp_f32_e32 v36, v36
	v_exp_f32_e32 v41, v41
	v_exp_f32_e32 v37, v37
	v_add_f32_e32 v38, 1.0, v38
	v_add_f32_e32 v34, 1.0, v34
	v_add_f32_e32 v39, 1.0, v39
	v_add_f32_e32 v35, 1.0, v35
	v_add_f32_e32 v40, 1.0, v40
	v_add_f32_e32 v36, 1.0, v36
	v_add_f32_e32 v41, 1.0, v41
	v_add_f32_e32 v37, 1.0, v37
	v_rcp_f32_e32 v38, v38
	v_rcp_f32_e32 v42, v34
	v_rcp_f32_e32 v34, v39
	v_rcp_f32_e32 v39, v35
	v_rcp_f32_e32 v35, v40
	v_rcp_f32_e32 v40, v41
	v_rcp_f32_e32 v41, v36
	v_rcp_f32_e32 v37, v37
	v_cvt_pk_bf16_f32 v34, v38, v34
	v_cvt_pk_bf16_f32 v35, v35, v40
	v_cvt_pk_bf16_f32 v36, v42, v39
	v_cvt_pk_bf16_f32 v37, v41, v37
	global_store_dwordx4 v[58:59], v[34:37], off offset:256
	s_nop 1
	v_mov_b64_e32 v[34:35], v[200:201]
	v_mov_b64_e32 v[36:37], v[202:203]
	v_mov_b64_e32 v[38:39], v[204:205]
	v_mov_b64_e32 v[40:41], v[206:207]
	v_add_u32_e32 v42, 0xa0, v148
	v_ashrrev_i32_e32 v43, 31, v42
	v_lshlrev_b64 v[42:43], 12, v[42:43]
	v_lshl_add_u64 v[42:43], s[18:19], 0, v[42:43]
	v_lshl_add_u64 v[42:43], v[42:43], 0, v[150:151]
	v_add_f32_e32 v30, v30, v34
	v_add_f32_e32 v26, v26, v38
	v_add_f32_e32 v31, v31, v35
	v_add_f32_e32 v27, v27, v39
	v_add_f32_e32 v32, v32, v36
	v_add_f32_e32 v28, v28, v40
	v_add_f32_e32 v33, v33, v37
	v_add_f32_e32 v29, v29, v41
	v_mul_f32_e32 v30, 0xbfb8aa3b, v30
	v_mul_f32_e32 v26, 0xbfb8aa3b, v26
	v_mul_f32_e32 v31, 0xbfb8aa3b, v31
	v_mul_f32_e32 v27, 0xbfb8aa3b, v27
	v_mul_f32_e32 v32, 0xbfb8aa3b, v32
	v_mul_f32_e32 v28, 0xbfb8aa3b, v28
	v_mul_f32_e32 v33, 0xbfb8aa3b, v33
	v_mul_f32_e32 v29, 0xbfb8aa3b, v29
	v_exp_f32_e32 v30, v30
	v_exp_f32_e32 v26, v26
	v_exp_f32_e32 v31, v31
	v_exp_f32_e32 v27, v27
	v_exp_f32_e32 v32, v32
	v_exp_f32_e32 v28, v28
	v_exp_f32_e32 v33, v33
	v_exp_f32_e32 v29, v29
	v_add_f32_e32 v30, 1.0, v30
	v_add_f32_e32 v26, 1.0, v26
	v_add_f32_e32 v31, 1.0, v31
	v_add_f32_e32 v27, 1.0, v27
	v_add_f32_e32 v32, 1.0, v32
	v_add_f32_e32 v28, 1.0, v28
	v_add_f32_e32 v33, 1.0, v33
	v_add_f32_e32 v29, 1.0, v29
	v_rcp_f32_e32 v30, v30
	v_rcp_f32_e32 v34, v26
	v_rcp_f32_e32 v26, v31
	v_rcp_f32_e32 v31, v27
	v_rcp_f32_e32 v27, v32
	v_rcp_f32_e32 v32, v33
	v_rcp_f32_e32 v33, v28
	v_rcp_f32_e32 v29, v29
	v_cvt_pk_bf16_f32 v26, v30, v26
	v_cvt_pk_bf16_f32 v27, v27, v32
	v_cvt_pk_bf16_f32 v28, v34, v31
	v_cvt_pk_bf16_f32 v29, v33, v29
	global_store_dwordx4 v[42:43], v[26:29], off
	s_nop 1
	v_mov_b64_e32 v[26:27], v[208:209]
; #define PG8_BAR __builtin_amdgcn_s_barrier()
; __device__ __forceinline__ float sigmoidf_(float z) { return __builtin_amdgcn_rcpf(1.f + __builtin_amdgcn_exp2f(-LOG2E_ * z)); }
; #define EPI_LOOP_END asm volatile("" ::: "memory"); } }
; __device__ __forceinline__ u32x4 pack8(const f32x4 a, const f32x4 b) { u32x4 w; w.x = pk2(a[0], a[1]); w.y = pk2(a[2], a[3]); w.z = pk2(b[0], b[1]); w.w = pk2(b[2], b[3]); return w; }
; template <class Epi, class Sched, bool ALIGN_EPI = false, bool SP2 = false>
; __device__ __forceinline__ void gemm_phase(PG8_LAS unsigned char* lds, const Gemm g, const Sched& S, const Epi& E) {
;     ...
;         if constexpr (ALIGN_EPI) { if (wr == 0) PG8_BAR; }
;         if constexpr (!Epi::AFTER_DRAIN) { E(acc, cur, wr, wc, fr, fq); S.done(cur); }
;         if (!has_next) break;
;     __device__ __forceinline__ void operator()(const f32x4 (&acc)[2][2][4][2], const Unit& u, int wr, int wc, int fr, int fq) const {
;     ...
;             const f32x4 b0 = *(const f32x4*)(bias + col), b1 = *(const f32x4*)(bias + col + 4); f32x4 a, b;
; #pragma unroll
;             for (int j = 0; j < 4; ++j) { a[j] = sigmoidf_(v0[j] + b0[j]); b[j] = sigmoidf_(v1[j] + b1[j]); if (MODE == 0) { a[j] *= -0.6065306597126334f; b[j] *= -0.6065306597126334f; } }
;             *(u32x4*)(O + (size_t)row * DM + col) = pack8(a, b);
;         EPI_LOOP_END
	v_mov_b64_e32 v[28:29], v[210:211]
	v_mov_b64_e32 v[30:31], v[212:213]
	v_mov_b64_e32 v[32:33], v[214:215]
	v_add_f32_e32 v22, v22, v26
	v_add_f32_e32 v18, v18, v30
	v_add_f32_e32 v23, v23, v27
	v_add_f32_e32 v19, v19, v31
	v_add_f32_e32 v24, v24, v28
	v_add_f32_e32 v20, v20, v32
	v_add_f32_e32 v25, v25, v29
	v_add_f32_e32 v21, v21, v33
	v_mul_f32_e32 v22, 0xbfb8aa3b, v22
	v_mul_f32_e32 v18, 0xbfb8aa3b, v18
	v_mul_f32_e32 v23, 0xbfb8aa3b, v23
	v_mul_f32_e32 v19, 0xbfb8aa3b, v19
	v_mul_f32_e32 v24, 0xbfb8aa3b, v24
	v_mul_f32_e32 v20, 0xbfb8aa3b, v20
	v_mul_f32_e32 v25, 0xbfb8aa3b, v25
	v_mul_f32_e32 v21, 0xbfb8aa3b, v21
	v_exp_f32_e32 v22, v22
	v_exp_f32_e32 v18, v18
	v_exp_f32_e32 v23, v23
	v_exp_f32_e32 v19, v19
	v_exp_f32_e32 v24, v24
	v_exp_f32_e32 v20, v20
	v_exp_f32_e32 v25, v25
	v_exp_f32_e32 v21, v21
	v_add_f32_e32 v22, 1.0, v22
	v_add_f32_e32 v18, 1.0, v18
	v_add_f32_e32 v23, 1.0, v23
	v_add_f32_e32 v19, 1.0, v19
	v_add_f32_e32 v24, 1.0, v24
	v_add_f32_e32 v20, 1.0, v20
	v_add_f32_e32 v25, 1.0, v25
	v_add_f32_e32 v21, 1.0, v21
	v_rcp_f32_e32 v22, v22
	v_rcp_f32_e32 v26, v18
	v_rcp_f32_e32 v18, v23
	v_rcp_f32_e32 v23, v19
	v_rcp_f32_e32 v19, v24
	v_rcp_f32_e32 v24, v25
	v_rcp_f32_e32 v25, v20
	v_rcp_f32_e32 v21, v21
	v_cvt_pk_bf16_f32 v18, v22, v18
	v_cvt_pk_bf16_f32 v19, v19, v24
	v_cvt_pk_bf16_f32 v20, v26, v23
	v_cvt_pk_bf16_f32 v21, v25, v21
	global_store_dwordx4 v[42:43], v[18:21], off offset:256
	s_nop 1
	v_mov_b64_e32 v[18:19], v[200:201]
	v_mov_b64_e32 v[20:21], v[202:203]
	v_mov_b64_e32 v[22:23], v[204:205]
	v_mov_b64_e32 v[24:25], v[206:207]
	v_add_u32_e32 v26, 0xb0, v148
	v_ashrrev_i32_e32 v27, 31, v26
	v_lshlrev_b64 v[26:27], 12, v[26:27]
	v_lshl_add_u64 v[26:27], s[18:19], 0, v[26:27]
	v_lshl_add_u64 v[26:27], v[26:27], 0, v[150:151]
	v_add_f32_e32 v14, v14, v18
	v_add_f32_e32 v10, v10, v22
	v_add_f32_e32 v15, v15, v19
	v_add_f32_e32 v11, v11, v23
	v_add_f32_e32 v16, v16, v20
	v_add_f32_e32 v12, v12, v24
	v_add_f32_e32 v17, v17, v21
	v_add_f32_e32 v13, v13, v25
	v_mul_f32_e32 v14, 0xbfb8aa3b, v14
	v_mul_f32_e32 v10, 0xbfb8aa3b, v10
	v_mul_f32_e32 v15, 0xbfb8aa3b, v15
	v_mul_f32_e32 v11, 0xbfb8aa3b, v11
	v_mul_f32_e32 v16, 0xbfb8aa3b, v16
	v_mul_f32_e32 v12, 0xbfb8aa3b, v12
	v_mul_f32_e32 v17, 0xbfb8aa3b, v17
	v_mul_f32_e32 v13, 0xbfb8aa3b, v13
	v_exp_f32_e32 v14, v14
	v_exp_f32_e32 v10, v10
	v_exp_f32_e32 v15, v15
	v_exp_f32_e32 v11, v11
	v_exp_f32_e32 v16, v16
	v_exp_f32_e32 v12, v12
	v_exp_f32_e32 v17, v17
	v_exp_f32_e32 v13, v13
	v_add_f32_e32 v14, 1.0, v14
	v_add_f32_e32 v10, 1.0, v10
	v_add_f32_e32 v15, 1.0, v15
	v_add_f32_e32 v11, 1.0, v11
	v_add_f32_e32 v16, 1.0, v16
	v_add_f32_e32 v12, 1.0, v12
	v_add_f32_e32 v17, 1.0, v17
	v_add_f32_e32 v13, 1.0, v13
	v_rcp_f32_e32 v14, v14
	v_rcp_f32_e32 v18, v10
	v_rcp_f32_e32 v10, v15
	v_rcp_f32_e32 v15, v11
	v_rcp_f32_e32 v11, v16
	v_rcp_f32_e32 v16, v17
	v_rcp_f32_e32 v17, v12
	v_rcp_f32_e32 v13, v13
	v_cvt_pk_bf16_f32 v10, v14, v10
	v_cvt_pk_bf16_f32 v11, v11, v16
	v_cvt_pk_bf16_f32 v12, v18, v15
	v_cvt_pk_bf16_f32 v13, v17, v13
	global_store_dwordx4 v[26:27], v[10:13], off
	s_nop 1
	v_mov_b64_e32 v[10:11], v[208:209]
	v_mov_b64_e32 v[12:13], v[210:211]
	v_mov_b64_e32 v[14:15], v[212:213]
	v_mov_b64_e32 v[16:17], v[214:215]
	v_add_f32_e32 v6, v6, v10
	v_add_f32_e32 v2, v2, v14
	v_add_f32_e32 v7, v7, v11
	v_add_f32_e32 v3, v3, v15
	v_add_f32_e32 v8, v8, v12
	v_add_f32_e32 v4, v4, v16
	v_add_f32_e32 v9, v9, v13
	v_add_f32_e32 v5, v5, v17
	v_mul_f32_e32 v6, 0xbfb8aa3b, v6
	v_mul_f32_e32 v2, 0xbfb8aa3b, v2
	v_mul_f32_e32 v7, 0xbfb8aa3b, v7
	v_mul_f32_e32 v3, 0xbfb8aa3b, v3
	v_mul_f32_e32 v8, 0xbfb8aa3b, v8
	v_mul_f32_e32 v4, 0xbfb8aa3b, v4
	v_mul_f32_e32 v9, 0xbfb8aa3b, v9
	v_mul_f32_e32 v5, 0xbfb8aa3b, v5
	v_exp_f32_e32 v6, v6
	v_exp_f32_e32 v2, v2
	v_exp_f32_e32 v7, v7
	v_exp_f32_e32 v3, v3
	v_exp_f32_e32 v8, v8
	v_exp_f32_e32 v4, v4
	v_exp_f32_e32 v9, v9
	v_exp_f32_e32 v5, v5
	v_add_f32_e32 v6, 1.0, v6
	v_add_f32_e32 v2, 1.0, v2
	v_add_f32_e32 v7, 1.0, v7
	v_add_f32_e32 v3, 1.0, v3
	v_add_f32_e32 v8, 1.0, v8
	v_add_f32_e32 v4, 1.0, v4
	v_add_f32_e32 v9, 1.0, v9
	v_add_f32_e32 v5, 1.0, v5
	v_rcp_f32_e32 v6, v6
	v_rcp_f32_e32 v10, v2
	v_rcp_f32_e32 v2, v7
	v_rcp_f32_e32 v7, v3
	v_rcp_f32_e32 v3, v8
	v_rcp_f32_e32 v8, v9
	v_rcp_f32_e32 v9, v4
	v_rcp_f32_e32 v5, v5
	v_cvt_pk_bf16_f32 v2, v6, v2
	v_cvt_pk_bf16_f32 v3, v3, v8
	v_cvt_pk_bf16_f32 v4, v10, v7
	v_cvt_pk_bf16_f32 v5, v9, v5
	global_store_dwordx4 v[26:27], v[2:5], off offset:256
	s_cbranch_vccnz .LBB0_1535
	s_andn2_b64 vcc, exec, s[14:15]
	s_cbranch_vccnz .LBB0_1534
	s_barrier
	s_branch .LBB0_1534
